# v10 + both residual GEMM epilogues rewritten by hand (16 residual loads hoisted before the epilogue barrier, batched shuffles, single masked store block)
# speedup vs baseline: 1.0130x; 1.0130x over previous
; #define PG8_STAGE(bufoff, gbase, voff) do { _Pragma("unroll") for (int _i = 0; _i < 2; ++_i) \
;         __builtin_amdgcn_global_load_lds((const unsigned*)((const char*)(gbase) + (voff)[_i]), (PG8_LAS unsigned*)(lds + (bufoff) + ldsw + _i * 8192), 16, 0, 0); } while (0)
; #define PG8_LDA(dst, b, h) do { _Pragma("unroll") for (int m = 0; m < 4; ++m) _Pragma("unroll") for (int k = 0; k < 2; ++k) dst[m][k] = *(const PG8_LAS bf16x8*)(lds + PG8_SA(b, h) + aoff + m * 2048 + k * 1024); } while (0)
; #define PG8_LDB(dst, b, h) do { _Pragma("unroll") for (int n = 0; n < 2; ++n) _Pragma("unroll") for (int k = 0; k < 2; ++k) dst[n][k] = *(const PG8_LAS bf16x8*)(lds + PG8_SB(b, h) + boff + n * 2048 + k * 1024); } while (0)
; #define PG8_MMA(ai, bj, At, Bt) do { __builtin_amdgcn_s_setprio(1); _Pragma("unroll") for (int m = 0; m < 4; ++m) _Pragma("unroll") for (int n = 0; n < 2; ++n) _Pragma("unroll") for (int k = 0; k < 2; ++k) \
;         acc[ai][bj][m][n] = __builtin_amdgcn_mfma_f32_16x16x32_bf16(Bt[n][k], At[m][k], acc[ai][bj][m][n], 0, 0, 0); __builtin_amdgcn_s_setprio(0); } while (0)
; #define PG8_WAIT_V(n) asm volatile("s_waitcnt vmcnt(" #n ")" ::: "memory")
; #define PG8_WAIT_L(n) asm volatile("s_waitcnt lgkmcnt(" #n ")" ::: "memory")
; #define PG8_BAR __builtin_amdgcn_s_barrier()
; #define PG8_SCHED __builtin_amdgcn_sched_barrier(0)
; template <class Epi, class Sched, bool ALIGN_EPI = false, bool SP2 = false>
; __device__ __forceinline__ void gemm_phase(PG8_LAS unsigned char* lds, const Gemm g, const Sched& S, const Epi& E) {
;     ...
;             PG8_LDB(B0, 0, 0); PG8_LDB(B1, 0, 1); PG8_SCHED; PG8_LDA(At, 0, 0); PG8_STAGE(PG8_SA(1, 1), a1 + hstep, voffA);
;             PG8_WAIT_V(8); PG8_WAIT_L(0); PG8_BAR; PG8_MMA(0, 0, At, B0); PG8_MMA(0, 1, At, B1); PG8_BAR; PG8_SCHED;
;             PG8_LDA(At, 0, 1); PG8_STAGE(PG8_SB(0, 0), b2, voffB); PG8_STAGE(PG8_SB(0, 1), b2 + hstep, voffB); PG8_STAGE(PG8_SA(0, 0), a2, voffA);
;             PG8_WAIT_V(8); PG8_WAIT_L(0); PG8_BAR; PG8_MMA(1, 0, At, B0); PG8_MMA(1, 1, At, B1); PG8_BAR; PG8_SCHED;
.LBB0_42:
	s_add_i32 s46, s24, 2
	s_add_u32 s47, s22, 0x80
	s_addc_u32 s25, s23, 0
	s_add_i32 s50, 0, 0x10000
	s_cmp_eq_u32 s37, s24
	s_cselect_b32 s25, s17, s25
	s_cselect_b32 s24, s42, s47
	s_cselect_b32 s49, s15, s45
	s_cselect_b32 s48, s43, s44
	s_add_i32 s47, 0, 0x14000
	v_add_u32_e32 v142, s50, v165
	v_add_u32_e32 v182, s47, v165
	ds_read_b128 v[130:133], v142
	ds_read_b128 v[134:137], v142 offset:1024
	ds_read_b128 v[138:141], v142 offset:2048
	ds_read_b128 v[142:145], v142 offset:3072
	ds_read_b128 v[146:149], v182
	ds_read_b128 v[150:153], v182 offset:1024
	ds_read_b128 v[154:157], v182 offset:2048
	ds_read_b128 v[182:185], v182 offset:3072
	v_lshl_add_u64 v[198:199], s[22:23], 0, v[178:179]
	s_add_i32 m0, s29, 0xc000
	ds_read_b128 v[186:189], v214
	ds_read_b128 v[190:193], v214 offset:1024
	ds_read_b128 v[194:197], v214 offset:2048
	ds_read_b128 v[216:219], v214 offset:3072
	ds_read_b128 v[220:223], v214 offset:4096
	ds_read_b128 v[224:227], v214 offset:5120
	ds_read_b128 v[228:231], v214 offset:6144
	ds_read_b128 v[232:235], v214 offset:7168
	global_load_lds_dwordx4 v[198:199], off
	v_lshl_add_u64 v[198:199], s[22:23], 0, v[180:181]
	s_add_i32 m0, s29, 0xe000
	s_nop 0
	global_load_lds_dwordx4 v[198:199], off
	s_waitcnt vmcnt(8)
	s_waitcnt lgkmcnt(0)
	s_barrier
	s_setprio 1
	s_waitcnt lgkmcnt(0)
	v_mfma_f32_16x16x32_bf16 v[126:129], v[130:133], v[186:189], v[126:129]
	v_mfma_f32_16x16x32_bf16 v[122:125], v[138:141], v[186:189], v[122:125]
	v_mfma_f32_16x16x32_bf16 v[110:113], v[130:133], v[194:197], v[110:113]
	v_mfma_f32_16x16x32_bf16 v[106:109], v[138:141], v[194:197], v[106:109]
	v_mfma_f32_16x16x32_bf16 v[94:97], v[130:133], v[220:223], v[94:97]
	v_mfma_f32_16x16x32_bf16 v[90:93], v[138:141], v[220:223], v[90:93]
	v_mfma_f32_16x16x32_bf16 v[78:81], v[130:133], v[228:231], v[78:81]
	v_mfma_f32_16x16x32_bf16 v[74:77], v[138:141], v[228:231], v[74:77]
	v_mfma_f32_16x16x32_bf16 v[126:129], v[134:137], v[190:193], v[126:129]
	v_mfma_f32_16x16x32_bf16 v[122:125], v[142:145], v[190:193], v[122:125]
	v_mfma_f32_16x16x32_bf16 v[110:113], v[134:137], v[216:219], v[110:113]
	v_mfma_f32_16x16x32_bf16 v[106:109], v[142:145], v[216:219], v[106:109]
	v_mfma_f32_16x16x32_bf16 v[94:97], v[134:137], v[224:227], v[94:97]
	v_mfma_f32_16x16x32_bf16 v[90:93], v[142:145], v[224:227], v[90:93]
	v_mfma_f32_16x16x32_bf16 v[78:81], v[134:137], v[232:235], v[78:81]
	v_mfma_f32_16x16x32_bf16 v[74:77], v[142:145], v[232:235], v[74:77]
	s_setprio 0
	s_setprio 1
	v_mfma_f32_16x16x32_bf16 v[118:121], v[146:149], v[186:189], v[118:121]
	v_mfma_f32_16x16x32_bf16 v[114:117], v[154:157], v[186:189], v[114:117]
	v_mfma_f32_16x16x32_bf16 v[102:105], v[146:149], v[194:197], v[102:105]
	v_mfma_f32_16x16x32_bf16 v[98:101], v[154:157], v[194:197], v[98:101]
	v_mfma_f32_16x16x32_bf16 v[86:89], v[146:149], v[220:223], v[86:89]
	v_mfma_f32_16x16x32_bf16 v[82:85], v[154:157], v[220:223], v[82:85]
	v_mfma_f32_16x16x32_bf16 v[70:73], v[146:149], v[228:231], v[70:73]
	v_mfma_f32_16x16x32_bf16 v[66:69], v[154:157], v[228:231], v[66:69]
	v_mfma_f32_16x16x32_bf16 v[118:121], v[150:153], v[190:193], v[118:121]
	v_mfma_f32_16x16x32_bf16 v[114:117], v[182:185], v[190:193], v[114:117]
	v_mfma_f32_16x16x32_bf16 v[102:105], v[150:153], v[216:219], v[102:105]
	v_mfma_f32_16x16x32_bf16 v[98:101], v[182:185], v[216:219], v[98:101]
	v_mfma_f32_16x16x32_bf16 v[86:89], v[150:153], v[224:227], v[86:89]
	v_mfma_f32_16x16x32_bf16 v[82:85], v[182:185], v[224:227], v[82:85]
	v_mfma_f32_16x16x32_bf16 v[70:73], v[150:153], v[232:235], v[70:73]
	v_mfma_f32_16x16x32_bf16 v[66:69], v[182:185], v[232:235], v[66:69]
	s_setprio 0
	s_barrier
	s_add_i32 s50, s50, s2
	v_lshl_add_u64 v[198:199], s[48:49], 0, v[0:1]
	s_mov_b32 m0, s50
	ds_read_b128 v[186:189], v214 offset:16384
	ds_read_b128 v[190:193], v214 offset:17408
	ds_read_b128 v[194:197], v214 offset:18432
	ds_read_b128 v[216:219], v214 offset:19456
	ds_read_b128 v[220:223], v214 offset:20480
	ds_read_b128 v[224:227], v214 offset:21504
	ds_read_b128 v[228:231], v214 offset:22528
	ds_read_b128 v[232:235], v214 offset:23552
	global_load_lds_dwordx4 v[198:199], off
	s_add_i32 m0, s50, 0x2000
	v_lshl_add_u64 v[236:237], s[48:49], 0, v[172:173]
	s_add_u32 s48, s48, s8
	s_addc_u32 s49, s49, 0
	s_add_i32 s47, s47, s2
	global_load_lds_dwordx4 v[236:237], off
	v_lshl_add_u64 v[238:239], s[48:49], 0, v[0:1]
	s_mov_b32 m0, s47
	v_lshl_add_u64 v[240:241], s[48:49], 0, v[172:173]
	global_load_lds_dwordx4 v[238:239], off
	s_add_i32 m0, s47, 0x2000
	v_lshl_add_u64 v[242:243], s[24:25], 0, v[176:177]
	global_load_lds_dwordx4 v[240:241], off
	s_mov_b32 m0, s29
	v_lshl_add_u64 v[244:245], s[24:25], 0, v[174:175]
	global_load_lds_dwordx4 v[242:243], off
	s_mov_b32 m0, s30
	s_nop 0
	global_load_lds_dwordx4 v[244:245], off
	s_waitcnt vmcnt(8)
	s_waitcnt lgkmcnt(0)
	s_barrier
; #define PG8_STAGE(bufoff, gbase, voff) do { _Pragma("unroll") for (int _i = 0; _i < 2; ++_i) \
;         __builtin_amdgcn_global_load_lds((const unsigned*)((const char*)(gbase) + (voff)[_i]), (PG8_LAS unsigned*)(lds + (bufoff) + ldsw + _i * 8192), 16, 0, 0); } while (0)
; #define PG8_LDA(dst, b, h) do { _Pragma("unroll") for (int m = 0; m < 4; ++m) _Pragma("unroll") for (int k = 0; k < 2; ++k) dst[m][k] = *(const PG8_LAS bf16x8*)(lds + PG8_SA(b, h) + aoff + m * 2048 + k * 1024); } while (0)
; #define PG8_LDB(dst, b, h) do { _Pragma("unroll") for (int n = 0; n < 2; ++n) _Pragma("unroll") for (int k = 0; k < 2; ++k) dst[n][k] = *(const PG8_LAS bf16x8*)(lds + PG8_SB(b, h) + boff + n * 2048 + k * 1024); } while (0)
; #define PG8_MMA(ai, bj, At, Bt) do { __builtin_amdgcn_s_setprio(1); _Pragma("unroll") for (int m = 0; m < 4; ++m) _Pragma("unroll") for (int n = 0; n < 2; ++n) _Pragma("unroll") for (int k = 0; k < 2; ++k) \
;         acc[ai][bj][m][n] = __builtin_amdgcn_mfma_f32_16x16x32_bf16(Bt[n][k], At[m][k], acc[ai][bj][m][n], 0, 0, 0); __builtin_amdgcn_s_setprio(0); } while (0)
; #define PG8_WAIT_V(n) asm volatile("s_waitcnt vmcnt(" #n ")" ::: "memory")
; #define PG8_WAIT_L(n) asm volatile("s_waitcnt lgkmcnt(" #n ")" ::: "memory")
; #define PG8_BAR __builtin_amdgcn_s_barrier()
; #define PG8_SCHED __builtin_amdgcn_sched_barrier(0)
; template <class Epi, class Sched, bool ALIGN_EPI = false, bool SP2 = false>
; __device__ __forceinline__ void gemm_phase(PG8_LAS unsigned char* lds, const Gemm g, const Sched& S, const Epi& E) {
;     ...
;             PG8_WAIT_V(8); PG8_WAIT_L(0); PG8_BAR; PG8_MMA(1, 0, At, B0); PG8_MMA(1, 1, At, B1); PG8_BAR; PG8_SCHED;
;             PG8_LDB(B0, 1, 0); PG8_LDB(B1, 1, 1); PG8_SCHED; PG8_LDA(At, 1, 0); PG8_STAGE(PG8_SA(0, 1), a2 + hstep, voffA);
;             PG8_WAIT_V(8); PG8_WAIT_L(0); PG8_BAR; PG8_MMA(0, 0, At, B0); PG8_MMA(0, 1, At, B1); PG8_BAR; PG8_SCHED;
	s_setprio 1
	s_waitcnt lgkmcnt(0)
	v_mfma_f32_16x16x32_bf16 v[62:65], v[130:133], v[186:189], v[62:65]
	v_mfma_f32_16x16x32_bf16 v[58:61], v[138:141], v[186:189], v[58:61]
	v_mfma_f32_16x16x32_bf16 v[46:49], v[130:133], v[194:197], v[46:49]
	v_mfma_f32_16x16x32_bf16 v[42:45], v[138:141], v[194:197], v[42:45]
	v_mfma_f32_16x16x32_bf16 v[30:33], v[130:133], v[220:223], v[30:33]
	v_mfma_f32_16x16x32_bf16 v[26:29], v[138:141], v[220:223], v[26:29]
	v_mfma_f32_16x16x32_bf16 v[14:17], v[130:133], v[228:231], v[14:17]
	v_mfma_f32_16x16x32_bf16 v[10:13], v[138:141], v[228:231], v[10:13]
	v_mfma_f32_16x16x32_bf16 v[62:65], v[134:137], v[190:193], v[62:65]
	v_mfma_f32_16x16x32_bf16 v[58:61], v[142:145], v[190:193], v[58:61]
	v_mfma_f32_16x16x32_bf16 v[46:49], v[134:137], v[216:219], v[46:49]
	v_mfma_f32_16x16x32_bf16 v[42:45], v[142:145], v[216:219], v[42:45]
	v_mfma_f32_16x16x32_bf16 v[30:33], v[134:137], v[224:227], v[30:33]
	v_mfma_f32_16x16x32_bf16 v[26:29], v[142:145], v[224:227], v[26:29]
	v_mfma_f32_16x16x32_bf16 v[14:17], v[134:137], v[232:235], v[14:17]
	v_mfma_f32_16x16x32_bf16 v[10:13], v[142:145], v[232:235], v[10:13]
	s_setprio 0
	s_setprio 1
	v_mfma_f32_16x16x32_bf16 v[54:57], v[146:149], v[186:189], v[54:57]
	v_mfma_f32_16x16x32_bf16 v[50:53], v[154:157], v[186:189], v[50:53]
	v_mfma_f32_16x16x32_bf16 v[38:41], v[146:149], v[194:197], v[38:41]
	v_mfma_f32_16x16x32_bf16 v[34:37], v[154:157], v[194:197], v[34:37]
	v_mfma_f32_16x16x32_bf16 v[22:25], v[146:149], v[220:223], v[22:25]
	v_mfma_f32_16x16x32_bf16 v[18:21], v[154:157], v[220:223], v[18:21]
	v_mfma_f32_16x16x32_bf16 v[6:9], v[146:149], v[228:231], v[6:9]
	v_mfma_f32_16x16x32_bf16 v[2:5], v[154:157], v[228:231], v[2:5]
	v_mfma_f32_16x16x32_bf16 v[54:57], v[150:153], v[190:193], v[54:57]
	v_mfma_f32_16x16x32_bf16 v[50:53], v[182:185], v[190:193], v[50:53]
	v_mfma_f32_16x16x32_bf16 v[38:41], v[150:153], v[216:219], v[38:41]
	v_mfma_f32_16x16x32_bf16 v[34:37], v[182:185], v[216:219], v[34:37]
	v_mfma_f32_16x16x32_bf16 v[22:25], v[150:153], v[224:227], v[22:25]
	v_mfma_f32_16x16x32_bf16 v[18:21], v[182:185], v[224:227], v[18:21]
	v_mfma_f32_16x16x32_bf16 v[6:9], v[150:153], v[232:235], v[6:9]
	v_mfma_f32_16x16x32_bf16 v[2:5], v[182:185], v[232:235], v[2:5]
	s_setprio 0
	s_barrier
	s_add_i32 s47, 0, 0x18000
	s_add_i32 s48, 0, 0x1c000
	v_add_u32_e32 v142, s47, v165
	v_add_u32_e32 v182, s48, v165
	ds_read_b128 v[130:133], v142
	ds_read_b128 v[134:137], v142 offset:1024
	ds_read_b128 v[138:141], v142 offset:2048
	ds_read_b128 v[142:145], v142 offset:3072
	ds_read_b128 v[146:149], v182
	ds_read_b128 v[150:153], v182 offset:1024
	ds_read_b128 v[154:157], v182 offset:2048
	ds_read_b128 v[182:185], v182 offset:3072
	s_add_u32 s24, s24, s8
	s_addc_u32 s25, s25, 0
	s_mov_b32 m0, s31
	v_lshl_add_u64 v[246:247], s[24:25], 0, v[176:177]
	ds_read_b128 v[186:189], v214 offset:32768
	ds_read_b128 v[190:193], v214 offset:33792
	ds_read_b128 v[194:197], v214 offset:34816
	ds_read_b128 v[216:219], v214 offset:35840
	ds_read_b128 v[220:223], v214 offset:36864
	ds_read_b128 v[224:227], v214 offset:37888
	ds_read_b128 v[228:231], v214 offset:38912
	ds_read_b128 v[232:235], v214 offset:39936
	global_load_lds_dwordx4 v[246:247], off
	v_lshl_add_u64 v[246:247], s[24:25], 0, v[174:175]
	s_mov_b32 m0, s34
	s_nop 0
	global_load_lds_dwordx4 v[246:247], off
	s_waitcnt vmcnt(8)
	s_waitcnt lgkmcnt(0)
	s_barrier
	s_setprio 1
	s_waitcnt lgkmcnt(0)
	v_mfma_f32_16x16x32_bf16 v[126:129], v[130:133], v[186:189], v[126:129]
	v_mfma_f32_16x16x32_bf16 v[122:125], v[138:141], v[186:189], v[122:125]
	v_mfma_f32_16x16x32_bf16 v[110:113], v[130:133], v[194:197], v[110:113]
	v_mfma_f32_16x16x32_bf16 v[106:109], v[138:141], v[194:197], v[106:109]
	v_mfma_f32_16x16x32_bf16 v[94:97], v[130:133], v[220:223], v[94:97]
	v_mfma_f32_16x16x32_bf16 v[90:93], v[138:141], v[220:223], v[90:93]
	v_mfma_f32_16x16x32_bf16 v[78:81], v[130:133], v[228:231], v[78:81]
	v_mfma_f32_16x16x32_bf16 v[74:77], v[138:141], v[228:231], v[74:77]
	v_mfma_f32_16x16x32_bf16 v[126:129], v[134:137], v[190:193], v[126:129]
	v_mfma_f32_16x16x32_bf16 v[122:125], v[142:145], v[190:193], v[122:125]
	v_mfma_f32_16x16x32_bf16 v[110:113], v[134:137], v[216:219], v[110:113]
	v_mfma_f32_16x16x32_bf16 v[106:109], v[142:145], v[216:219], v[106:109]
	v_mfma_f32_16x16x32_bf16 v[94:97], v[134:137], v[224:227], v[94:97]
	v_mfma_f32_16x16x32_bf16 v[90:93], v[142:145], v[224:227], v[90:93]
	v_mfma_f32_16x16x32_bf16 v[78:81], v[134:137], v[232:235], v[78:81]
	v_mfma_f32_16x16x32_bf16 v[74:77], v[142:145], v[232:235], v[74:77]
	s_setprio 0
	s_setprio 1
	v_mfma_f32_16x16x32_bf16 v[118:121], v[146:149], v[186:189], v[118:121]
	v_mfma_f32_16x16x32_bf16 v[114:117], v[154:157], v[186:189], v[114:117]
	v_mfma_f32_16x16x32_bf16 v[102:105], v[146:149], v[194:197], v[102:105]
	v_mfma_f32_16x16x32_bf16 v[98:101], v[154:157], v[194:197], v[98:101]
	v_mfma_f32_16x16x32_bf16 v[86:89], v[146:149], v[220:223], v[86:89]
	v_mfma_f32_16x16x32_bf16 v[82:85], v[154:157], v[220:223], v[82:85]
	v_mfma_f32_16x16x32_bf16 v[70:73], v[146:149], v[228:231], v[70:73]
	v_mfma_f32_16x16x32_bf16 v[66:69], v[154:157], v[228:231], v[66:69]
	v_mfma_f32_16x16x32_bf16 v[118:121], v[150:153], v[190:193], v[118:121]
	v_mfma_f32_16x16x32_bf16 v[114:117], v[182:185], v[190:193], v[114:117]
	v_mfma_f32_16x16x32_bf16 v[102:105], v[150:153], v[216:219], v[102:105]
	v_mfma_f32_16x16x32_bf16 v[98:101], v[182:185], v[216:219], v[98:101]
	v_mfma_f32_16x16x32_bf16 v[86:89], v[150:153], v[224:227], v[86:89]
	v_mfma_f32_16x16x32_bf16 v[82:85], v[182:185], v[224:227], v[82:85]
	v_mfma_f32_16x16x32_bf16 v[70:73], v[150:153], v[232:235], v[70:73]
	v_mfma_f32_16x16x32_bf16 v[66:69], v[182:185], v[232:235], v[66:69]
	s_setprio 0
	s_barrier
; #define PG8_STAGE(bufoff, gbase, voff) do { _Pragma("unroll") for (int _i = 0; _i < 2; ++_i) \
;         __builtin_amdgcn_global_load_lds((const unsigned*)((const char*)(gbase) + (voff)[_i]), (PG8_LAS unsigned*)(lds + (bufoff) + ldsw + _i * 8192), 16, 0, 0); } while (0)
; #define PG8_LDA(dst, b, h) do { _Pragma("unroll") for (int m = 0; m < 4; ++m) _Pragma("unroll") for (int k = 0; k < 2; ++k) dst[m][k] = *(const PG8_LAS bf16x8*)(lds + PG8_SA(b, h) + aoff + m * 2048 + k * 1024); } while (0)
; #define PG8_MMA(ai, bj, At, Bt) do { __builtin_amdgcn_s_setprio(1); _Pragma("unroll") for (int m = 0; m < 4; ++m) _Pragma("unroll") for (int n = 0; n < 2; ++n) _Pragma("unroll") for (int k = 0; k < 2; ++k) \
;         acc[ai][bj][m][n] = __builtin_amdgcn_mfma_f32_16x16x32_bf16(Bt[n][k], At[m][k], acc[ai][bj][m][n], 0, 0, 0); __builtin_amdgcn_s_setprio(0); } while (0)
; #define PG8_WAIT_V(n) asm volatile("s_waitcnt vmcnt(" #n ")" ::: "memory")
; #define PG8_WAIT_L(n) asm volatile("s_waitcnt lgkmcnt(" #n ")" ::: "memory")
; #define PG8_BAR __builtin_amdgcn_s_barrier()
; #define PG8_SCHED __builtin_amdgcn_sched_barrier(0)
; template <class Epi, class Sched, bool ALIGN_EPI = false, bool SP2 = false>
; __device__ __forceinline__ void gemm_phase(PG8_LAS unsigned char* lds, const Gemm g, const Sched& S, const Epi& E) {
;     ...
;             PG8_LDA(At, 1, 1); PG8_STAGE(PG8_SB(1, 0), b3, voffB); PG8_STAGE(PG8_SB(1, 1), b3 + hstep, voffB); PG8_STAGE(PG8_SA(1, 0), a3, voffA);
;             PG8_WAIT_V(8); PG8_WAIT_L(0); PG8_BAR; PG8_MMA(1, 0, At, B0); PG8_MMA(1, 1, At, B1); PG8_BAR; PG8_SCHED;
;     __device__ __forceinline__ void operator()(const f32x4 (&acc)[2][2][4][2], const Unit& u, int wr, int wc, int fr, int fq) const {
;         const int row0 = u.pm * BM + wr * 64 + fr, col0 = u.pn * BM + wc * 32 + 8 * fq;
; #pragma unroll
;         for (int ai = 0; ai < 2; ++ai) {
;             u32x4 xv[4][2];
; #pragma unroll
;             for (int m = 0; m < 4; ++m)
; #pragma unroll
;                 for (int bj = 0; bj < 2; ++bj) xv[m][bj] = *(const u32x4*)(XB + (size_t)(row0 + ai * HALF + m * 16) * 1024 + col0 + bj * HALF);
;             asm volatile("" ::: "memory");
	s_add_i32 s24, s47, s2
	v_lshl_add_u64 v[198:199], v[198:199], 0, s[90:91]
	s_mov_b32 m0, s24
	ds_read_b128 v[186:189], v214 offset:49152
	ds_read_b128 v[190:193], v214 offset:50176
	ds_read_b128 v[194:197], v214 offset:51200
	ds_read_b128 v[216:219], v214 offset:52224
	ds_read_b128 v[220:223], v214 offset:53248
	ds_read_b128 v[224:227], v214 offset:54272
	ds_read_b128 v[228:231], v214 offset:55296
	ds_read_b128 v[232:235], v214 offset:56320
	global_load_lds_dwordx4 v[198:199], off
	v_lshl_add_u64 v[198:199], v[236:237], 0, s[90:91]
	s_add_i32 m0, s24, 0x2000
	s_add_i32 s24, s48, s2
	global_load_lds_dwordx4 v[198:199], off
	v_lshl_add_u64 v[198:199], v[238:239], 0, s[90:91]
	s_mov_b32 m0, s24
	s_nop 0
	global_load_lds_dwordx4 v[198:199], off
	v_lshl_add_u64 v[198:199], v[240:241], 0, s[90:91]
	s_add_i32 m0, s24, 0x2000
	s_nop 0
	global_load_lds_dwordx4 v[198:199], off
	v_lshl_add_u64 v[198:199], v[242:243], 0, s[90:91]
	s_mov_b32 m0, s38
	s_nop 0
	global_load_lds_dwordx4 v[198:199], off
	v_lshl_add_u64 v[198:199], v[244:245], 0, s[90:91]
	s_mov_b32 m0, s39
	s_nop 0
	global_load_lds_dwordx4 v[198:199], off
	s_waitcnt vmcnt(8)
	s_waitcnt lgkmcnt(0)
	s_barrier
	s_setprio 1
	s_waitcnt lgkmcnt(0)
	v_mfma_f32_16x16x32_bf16 v[62:65], v[130:133], v[186:189], v[62:65]
	v_mfma_f32_16x16x32_bf16 v[58:61], v[138:141], v[186:189], v[58:61]
	v_mfma_f32_16x16x32_bf16 v[46:49], v[130:133], v[194:197], v[46:49]
	v_mfma_f32_16x16x32_bf16 v[42:45], v[138:141], v[194:197], v[42:45]
	v_mfma_f32_16x16x32_bf16 v[30:33], v[130:133], v[220:223], v[30:33]
	v_mfma_f32_16x16x32_bf16 v[26:29], v[138:141], v[220:223], v[26:29]
	v_mfma_f32_16x16x32_bf16 v[14:17], v[130:133], v[228:231], v[14:17]
	v_mfma_f32_16x16x32_bf16 v[10:13], v[138:141], v[228:231], v[10:13]
	v_mfma_f32_16x16x32_bf16 v[62:65], v[134:137], v[190:193], v[62:65]
	v_mfma_f32_16x16x32_bf16 v[58:61], v[142:145], v[190:193], v[58:61]
	v_mfma_f32_16x16x32_bf16 v[46:49], v[134:137], v[216:219], v[46:49]
	v_mfma_f32_16x16x32_bf16 v[42:45], v[142:145], v[216:219], v[42:45]
	v_mfma_f32_16x16x32_bf16 v[30:33], v[134:137], v[224:227], v[30:33]
	v_mfma_f32_16x16x32_bf16 v[26:29], v[142:145], v[224:227], v[26:29]
	v_mfma_f32_16x16x32_bf16 v[14:17], v[134:137], v[232:235], v[14:17]
	v_mfma_f32_16x16x32_bf16 v[10:13], v[142:145], v[232:235], v[10:13]
	s_setprio 0
	s_setprio 1
	v_mfma_f32_16x16x32_bf16 v[54:57], v[146:149], v[186:189], v[54:57]
	v_mfma_f32_16x16x32_bf16 v[50:53], v[154:157], v[186:189], v[50:53]
	v_mfma_f32_16x16x32_bf16 v[38:41], v[146:149], v[194:197], v[38:41]
	v_mfma_f32_16x16x32_bf16 v[34:37], v[154:157], v[194:197], v[34:37]
	v_mfma_f32_16x16x32_bf16 v[22:25], v[146:149], v[220:223], v[22:25]
	v_mfma_f32_16x16x32_bf16 v[18:21], v[154:157], v[220:223], v[18:21]
	v_mfma_f32_16x16x32_bf16 v[6:9], v[146:149], v[228:231], v[6:9]
	v_mfma_f32_16x16x32_bf16 v[2:5], v[154:157], v[228:231], v[2:5]
	v_mfma_f32_16x16x32_bf16 v[54:57], v[150:153], v[190:193], v[54:57]
	v_mfma_f32_16x16x32_bf16 v[50:53], v[182:185], v[190:193], v[50:53]
	v_mfma_f32_16x16x32_bf16 v[38:41], v[150:153], v[216:219], v[38:41]
	v_mfma_f32_16x16x32_bf16 v[34:37], v[182:185], v[216:219], v[34:37]
	v_mfma_f32_16x16x32_bf16 v[22:25], v[150:153], v[224:227], v[22:25]
	v_mfma_f32_16x16x32_bf16 v[18:21], v[182:185], v[224:227], v[18:21]
	v_mfma_f32_16x16x32_bf16 v[6:9], v[150:153], v[232:235], v[6:9]
	v_mfma_f32_16x16x32_bf16 v[2:5], v[182:185], v[232:235], v[2:5]
	s_setprio 0
	s_barrier
	s_add_u32 s22, s22, 0x100
	s_addc_u32 s23, s23, 0
	s_add_u32 s44, s44, 0x100
	s_addc_u32 s45, s45, 0
	s_cmp_ge_u32 s46, s36
	s_mov_b32 s24, s46
	s_cbranch_scc0 .LBB0_42
	v_lshl_or_b32 v198, s9, 8, v213
	v_lshl_add_u32 v217, s41, 8, v158
	v_lshlrev_b32_e32 v246, 1, v198
	v_lshl_add_u32 v246, v217, 11, v246
	v_mov_b32_e32 v247, 0
	s_mov_b32 s22, 0x8000
	s_mov_b32 s23, 0
	s_mov_b32 s88, 0x28000
	v_lshl_add_u64 v[246:247], s[94:95], 0, v[246:247]
	v_xor_b32_e32 v215, 16, v201
	v_xor_b32_e32 v216, 32, v201
	v_mov_b32_e32 v198, v246
	v_mov_b32_e32 v199, v247
	global_load_dwordx4 v[130:133], v[246:247], off
	global_load_dwordx4 v[134:137], v[246:247], off offset:256
	v_lshl_add_u64 v[246:247], v[246:247], 0, s[22:23]
	global_load_dwordx4 v[138:141], v[246:247], off
	global_load_dwordx4 v[142:145], v[246:247], off offset:256
	v_lshl_add_u64 v[246:247], v[246:247], 0, s[22:23]
	global_load_dwordx4 v[146:149], v[246:247], off
	global_load_dwordx4 v[150:153], v[246:247], off offset:256
	v_lshl_add_u64 v[246:247], v[246:247], 0, s[22:23]
	global_load_dwordx4 v[154:157], v[246:247], off
	global_load_dwordx4 v[218:221], v[246:247], off offset:256
	v_lshl_add_u64 v[246:247], v[246:247], 0, s[88:89]
	global_load_dwordx4 v[182:185], v[246:247], off
	global_load_dwordx4 v[186:189], v[246:247], off offset:256
	v_lshl_add_u64 v[246:247], v[246:247], 0, s[22:23]
	global_load_dwordx4 v[190:193], v[246:247], off
	global_load_dwordx4 v[194:197], v[246:247], off offset:256
	v_lshl_add_u64 v[246:247], v[246:247], 0, s[22:23]
	global_load_dwordx4 v[222:225], v[246:247], off
	global_load_dwordx4 v[226:229], v[246:247], off offset:256
	v_lshl_add_u64 v[246:247], v[246:247], 0, s[22:23]
	global_load_dwordx4 v[230:233], v[246:247], off
	global_load_dwordx4 v[234:237], v[246:247], off offset:256
	v_lshlrev_b32_e32 v215, 2, v215
	v_lshlrev_b32_e32 v216, 2, v216
	s_and_b64 vcc, exec, s[12:13]
	s_cbranch_vccz .LBB0_45
	s_barrier
; __device__ __forceinline__ unsigned cvt_pk_bf16(float lo, float hi) { f32x2_cv v = {lo, hi}; bf16x2_cv b = __builtin_convertvector(v, bf16x2_cv); return __builtin_bit_cast(unsigned, b); }
;     __device__ __forceinline__ void operator()(const f32x4 (&acc)[2][2][4][2], const Unit& u, int wr, int wc, int fr, int fq) const {
;     ...
; #pragma unroll
;             for (int m = 0; m < 4; ++m) {
;                 const int row = row0 + ai * HALF + m * 16; float ss = 0.f;
; #pragma unroll
;                 for (int bj = 0; bj < 2; ++bj) {
;                     const size_t off = (size_t)row * 1024 + col0 + bj * HALF;
;                     const u32x4 v = xv[m][bj];
;                     f32x4 x0 = {__uint_as_float(v.x << 16), __uint_as_float(v.x & 0xffff0000u), __uint_as_float(v.y << 16), __uint_as_float(v.y & 0xffff0000u)};
;                     f32x4 x1 = {__uint_as_float(v.z << 16), __uint_as_float(v.z & 0xffff0000u), __uint_as_float(v.w << 16), __uint_as_float(v.w & 0xffff0000u)};
;                     x0 = x0 + acc[ai][bj][m][0] * alpha; x1 = x1 + acc[ai][bj][m][1] * alpha;
;                     u32x4 w; w.x = cvt_pk_bf16(x0[0], x0[1]); w.y = cvt_pk_bf16(x0[2], x0[3]); w.z = cvt_pk_bf16(x1[0], x1[1]); w.w = cvt_pk_bf16(x1[2], x1[3]);
;                     *(u32x4*)(XB + off) = w;
;                     const f32x4 sq = x0 * x0 + x1 * x1;
;                     ss += (sq[0] + sq[1]) + (sq[2] + sq[3]);
.LBB0_45:
	s_waitcnt vmcnt(15)
	v_lshlrev_b32_e32 v238, 16, v130
	v_and_b32_e32 v239, 0xffff0000, v130
	v_lshlrev_b32_e32 v240, 16, v131
	v_and_b32_e32 v241, 0xffff0000, v131
	v_lshlrev_b32_e32 v242, 16, v132
	v_and_b32_e32 v243, 0xffff0000, v132
	v_lshlrev_b32_e32 v244, 16, v133
	v_and_b32_e32 v245, 0xffff0000, v133
	v_pk_add_f32 v[126:127], v[126:127], v[238:239]
	v_pk_add_f32 v[128:129], v[128:129], v[240:241]
	v_pk_add_f32 v[122:123], v[122:123], v[242:243]
	v_pk_add_f32 v[124:125], v[124:125], v[244:245]
	v_cvt_pk_bf16_f32 v130, v126, v127
	v_cvt_pk_bf16_f32 v131, v128, v129
	v_cvt_pk_bf16_f32 v132, v122, v123
	v_cvt_pk_bf16_f32 v133, v124, v125
	global_store_dwordx4 v[198:199], v[130:133], off
	v_pk_mul_f32 v[238:239], v[122:123], v[122:123]
	v_pk_mul_f32 v[240:241], v[124:125], v[124:125]
	v_pk_fma_f32 v[238:239], v[126:127], v[126:127], v[238:239]
	v_pk_fma_f32 v[240:241], v[128:129], v[128:129], v[240:241]
	s_nop 0
	v_add_f32_e32 v238, v238, v239
	v_add_f32_e32 v239, v240, v241
	v_add_f32_e32 v126, v238, v239
	s_waitcnt vmcnt(15)
	v_lshlrev_b32_e32 v238, 16, v134
	v_and_b32_e32 v239, 0xffff0000, v134
	v_lshlrev_b32_e32 v240, 16, v135
	v_and_b32_e32 v241, 0xffff0000, v135
	v_lshlrev_b32_e32 v242, 16, v136
	v_and_b32_e32 v243, 0xffff0000, v136
	v_lshlrev_b32_e32 v244, 16, v137
	v_and_b32_e32 v245, 0xffff0000, v137
	v_pk_add_f32 v[118:119], v[118:119], v[238:239]
	v_pk_add_f32 v[120:121], v[120:121], v[240:241]
	v_pk_add_f32 v[114:115], v[114:115], v[242:243]
	v_pk_add_f32 v[116:117], v[116:117], v[244:245]
	v_cvt_pk_bf16_f32 v134, v118, v119
	v_cvt_pk_bf16_f32 v135, v120, v121
	v_cvt_pk_bf16_f32 v136, v114, v115
	v_cvt_pk_bf16_f32 v137, v116, v117
	global_store_dwordx4 v[198:199], v[134:137], off offset:256
	v_pk_mul_f32 v[238:239], v[114:115], v[114:115]
	v_pk_mul_f32 v[240:241], v[116:117], v[116:117]
	v_pk_fma_f32 v[238:239], v[118:119], v[118:119], v[238:239]
	v_pk_fma_f32 v[240:241], v[120:121], v[120:121], v[240:241]
	s_nop 0
	v_add_f32_e32 v238, v238, v239
	v_add_f32_e32 v239, v240, v241
	v_add_f32_e32 v238, v238, v239
	v_add_f32_e32 v126, v126, v238
	v_lshl_add_u64 v[198:199], v[198:199], 0, s[22:23]
	s_waitcnt vmcnt(15)
	v_lshlrev_b32_e32 v238, 16, v138
	v_and_b32_e32 v239, 0xffff0000, v138
	v_lshlrev_b32_e32 v240, 16, v139
	v_and_b32_e32 v241, 0xffff0000, v139
	v_lshlrev_b32_e32 v242, 16, v140
	v_and_b32_e32 v243, 0xffff0000, v140
	v_lshlrev_b32_e32 v244, 16, v141
	v_and_b32_e32 v245, 0xffff0000, v141
	v_pk_add_f32 v[110:111], v[110:111], v[238:239]
	v_pk_add_f32 v[112:113], v[112:113], v[240:241]
	v_pk_add_f32 v[106:107], v[106:107], v[242:243]
	v_pk_add_f32 v[108:109], v[108:109], v[244:245]
	v_cvt_pk_bf16_f32 v138, v110, v111
	v_cvt_pk_bf16_f32 v139, v112, v113
	v_cvt_pk_bf16_f32 v140, v106, v107
	v_cvt_pk_bf16_f32 v141, v108, v109
	global_store_dwordx4 v[198:199], v[138:141], off
	v_pk_mul_f32 v[238:239], v[106:107], v[106:107]
	v_pk_mul_f32 v[240:241], v[108:109], v[108:109]
	v_pk_fma_f32 v[238:239], v[110:111], v[110:111], v[238:239]
	v_pk_fma_f32 v[240:241], v[112:113], v[112:113], v[240:241]
	s_nop 0
	v_add_f32_e32 v238, v238, v239
	v_add_f32_e32 v239, v240, v241
	v_add_f32_e32 v110, v238, v239
	s_waitcnt vmcnt(15)
	v_lshlrev_b32_e32 v238, 16, v142
	v_and_b32_e32 v239, 0xffff0000, v142
	v_lshlrev_b32_e32 v240, 16, v143
	v_and_b32_e32 v241, 0xffff0000, v143
	v_lshlrev_b32_e32 v242, 16, v144
	v_and_b32_e32 v243, 0xffff0000, v144
	v_lshlrev_b32_e32 v244, 16, v145
	v_and_b32_e32 v245, 0xffff0000, v145
	v_pk_add_f32 v[102:103], v[102:103], v[238:239]
	v_pk_add_f32 v[104:105], v[104:105], v[240:241]
	v_pk_add_f32 v[98:99], v[98:99], v[242:243]
	v_pk_add_f32 v[100:101], v[100:101], v[244:245]
	v_cvt_pk_bf16_f32 v142, v102, v103
	v_cvt_pk_bf16_f32 v143, v104, v105
	v_cvt_pk_bf16_f32 v144, v98, v99
	v_cvt_pk_bf16_f32 v145, v100, v101
	global_store_dwordx4 v[198:199], v[142:145], off offset:256
	v_pk_mul_f32 v[238:239], v[98:99], v[98:99]
	v_pk_mul_f32 v[240:241], v[100:101], v[100:101]
	v_pk_fma_f32 v[238:239], v[102:103], v[102:103], v[238:239]
	v_pk_fma_f32 v[240:241], v[104:105], v[104:105], v[240:241]
	s_nop 0
	v_add_f32_e32 v238, v238, v239
	v_add_f32_e32 v239, v240, v241
	v_add_f32_e32 v238, v238, v239
	v_add_f32_e32 v110, v110, v238
	v_lshl_add_u64 v[198:199], v[198:199], 0, s[22:23]
	s_waitcnt vmcnt(15)
	v_lshlrev_b32_e32 v238, 16, v146
	v_and_b32_e32 v239, 0xffff0000, v146
	v_lshlrev_b32_e32 v240, 16, v147
	v_and_b32_e32 v241, 0xffff0000, v147
	v_lshlrev_b32_e32 v242, 16, v148
	v_and_b32_e32 v243, 0xffff0000, v148
	v_lshlrev_b32_e32 v244, 16, v149
	v_and_b32_e32 v245, 0xffff0000, v149
	v_pk_add_f32 v[94:95], v[94:95], v[238:239]
	v_pk_add_f32 v[96:97], v[96:97], v[240:241]
	v_pk_add_f32 v[90:91], v[90:91], v[242:243]
	v_pk_add_f32 v[92:93], v[92:93], v[244:245]
	v_cvt_pk_bf16_f32 v146, v94, v95
	v_cvt_pk_bf16_f32 v147, v96, v97
	v_cvt_pk_bf16_f32 v148, v90, v91
	v_cvt_pk_bf16_f32 v149, v92, v93
	global_store_dwordx4 v[198:199], v[146:149], off
	v_pk_mul_f32 v[238:239], v[90:91], v[90:91]
	v_pk_mul_f32 v[240:241], v[92:93], v[92:93]
	v_pk_fma_f32 v[238:239], v[94:95], v[94:95], v[238:239]
	v_pk_fma_f32 v[240:241], v[96:97], v[96:97], v[240:241]
	s_nop 0
	v_add_f32_e32 v238, v238, v239
	v_add_f32_e32 v239, v240, v241
	v_add_f32_e32 v94, v238, v239
	s_waitcnt vmcnt(15)
; __device__ __forceinline__ unsigned cvt_pk_bf16(float lo, float hi) { f32x2_cv v = {lo, hi}; bf16x2_cv b = __builtin_convertvector(v, bf16x2_cv); return __builtin_bit_cast(unsigned, b); }
;     __device__ __forceinline__ void operator()(const f32x4 (&acc)[2][2][4][2], const Unit& u, int wr, int wc, int fr, int fq) const {
;     ...
; #pragma unroll
;             for (int m = 0; m < 4; ++m) {
;                 const int row = row0 + ai * HALF + m * 16; float ss = 0.f;
; #pragma unroll
;                 for (int bj = 0; bj < 2; ++bj) {
;                     const size_t off = (size_t)row * 1024 + col0 + bj * HALF;
;                     const u32x4 v = xv[m][bj];
;                     f32x4 x0 = {__uint_as_float(v.x << 16), __uint_as_float(v.x & 0xffff0000u), __uint_as_float(v.y << 16), __uint_as_float(v.y & 0xffff0000u)};
;                     f32x4 x1 = {__uint_as_float(v.z << 16), __uint_as_float(v.z & 0xffff0000u), __uint_as_float(v.w << 16), __uint_as_float(v.w & 0xffff0000u)};
;                     x0 = x0 + acc[ai][bj][m][0] * alpha; x1 = x1 + acc[ai][bj][m][1] * alpha;
;                     u32x4 w; w.x = cvt_pk_bf16(x0[0], x0[1]); w.y = cvt_pk_bf16(x0[2], x0[3]); w.z = cvt_pk_bf16(x1[0], x1[1]); w.w = cvt_pk_bf16(x1[2], x1[3]);
;                     *(u32x4*)(XB + off) = w;
;                     const f32x4 sq = x0 * x0 + x1 * x1;
;                     ss += (sq[0] + sq[1]) + (sq[2] + sq[3]);
	v_lshlrev_b32_e32 v238, 16, v150
	v_and_b32_e32 v239, 0xffff0000, v150
	v_lshlrev_b32_e32 v240, 16, v151
	v_and_b32_e32 v241, 0xffff0000, v151
	v_lshlrev_b32_e32 v242, 16, v152
	v_and_b32_e32 v243, 0xffff0000, v152
	v_lshlrev_b32_e32 v244, 16, v153
	v_and_b32_e32 v245, 0xffff0000, v153
	v_pk_add_f32 v[86:87], v[86:87], v[238:239]
	v_pk_add_f32 v[88:89], v[88:89], v[240:241]
	v_pk_add_f32 v[82:83], v[82:83], v[242:243]
	v_pk_add_f32 v[84:85], v[84:85], v[244:245]
	v_cvt_pk_bf16_f32 v150, v86, v87
	v_cvt_pk_bf16_f32 v151, v88, v89
	v_cvt_pk_bf16_f32 v152, v82, v83
	v_cvt_pk_bf16_f32 v153, v84, v85
	global_store_dwordx4 v[198:199], v[150:153], off offset:256
	v_pk_mul_f32 v[238:239], v[82:83], v[82:83]
	v_pk_mul_f32 v[240:241], v[84:85], v[84:85]
	v_pk_fma_f32 v[238:239], v[86:87], v[86:87], v[238:239]
	v_pk_fma_f32 v[240:241], v[88:89], v[88:89], v[240:241]
	s_nop 0
	v_add_f32_e32 v238, v238, v239
	v_add_f32_e32 v239, v240, v241
	v_add_f32_e32 v238, v238, v239
	v_add_f32_e32 v94, v94, v238
	v_lshl_add_u64 v[198:199], v[198:199], 0, s[22:23]
	s_waitcnt vmcnt(15)
	v_lshlrev_b32_e32 v238, 16, v154
	v_and_b32_e32 v239, 0xffff0000, v154
	v_lshlrev_b32_e32 v240, 16, v155
	v_and_b32_e32 v241, 0xffff0000, v155
	v_lshlrev_b32_e32 v242, 16, v156
	v_and_b32_e32 v243, 0xffff0000, v156
	v_lshlrev_b32_e32 v244, 16, v157
	v_and_b32_e32 v245, 0xffff0000, v157
	v_pk_add_f32 v[78:79], v[78:79], v[238:239]
	v_pk_add_f32 v[80:81], v[80:81], v[240:241]
	v_pk_add_f32 v[74:75], v[74:75], v[242:243]
	v_pk_add_f32 v[76:77], v[76:77], v[244:245]
	v_cvt_pk_bf16_f32 v154, v78, v79
	v_cvt_pk_bf16_f32 v155, v80, v81
	v_cvt_pk_bf16_f32 v156, v74, v75
	v_cvt_pk_bf16_f32 v157, v76, v77
	global_store_dwordx4 v[198:199], v[154:157], off
	v_pk_mul_f32 v[238:239], v[74:75], v[74:75]
	v_pk_mul_f32 v[240:241], v[76:77], v[76:77]
	v_pk_fma_f32 v[238:239], v[78:79], v[78:79], v[238:239]
	v_pk_fma_f32 v[240:241], v[80:81], v[80:81], v[240:241]
	s_nop 0
	v_add_f32_e32 v238, v238, v239
	v_add_f32_e32 v239, v240, v241
	v_add_f32_e32 v78, v238, v239
	s_waitcnt vmcnt(15)
	v_lshlrev_b32_e32 v238, 16, v218
	v_and_b32_e32 v239, 0xffff0000, v218
	v_lshlrev_b32_e32 v240, 16, v219
	v_and_b32_e32 v241, 0xffff0000, v219
	v_lshlrev_b32_e32 v242, 16, v220
	v_and_b32_e32 v243, 0xffff0000, v220
	v_lshlrev_b32_e32 v244, 16, v221
	v_and_b32_e32 v245, 0xffff0000, v221
	v_pk_add_f32 v[70:71], v[70:71], v[238:239]
	v_pk_add_f32 v[72:73], v[72:73], v[240:241]
	v_pk_add_f32 v[66:67], v[66:67], v[242:243]
	v_pk_add_f32 v[68:69], v[68:69], v[244:245]
	v_cvt_pk_bf16_f32 v218, v70, v71
	v_cvt_pk_bf16_f32 v219, v72, v73
	v_cvt_pk_bf16_f32 v220, v66, v67
	v_cvt_pk_bf16_f32 v221, v68, v69
	global_store_dwordx4 v[198:199], v[218:221], off offset:256
	v_pk_mul_f32 v[238:239], v[66:67], v[66:67]
	v_pk_mul_f32 v[240:241], v[68:69], v[68:69]
	v_pk_fma_f32 v[238:239], v[70:71], v[70:71], v[238:239]
	v_pk_fma_f32 v[240:241], v[72:73], v[72:73], v[240:241]
	s_nop 0
	v_add_f32_e32 v238, v238, v239
	v_add_f32_e32 v239, v240, v241
	v_add_f32_e32 v238, v238, v239
	v_add_f32_e32 v78, v78, v238
	v_lshl_add_u64 v[198:199], v[198:199], 0, s[88:89]
	s_waitcnt vmcnt(15)
	v_lshlrev_b32_e32 v238, 16, v182
	v_and_b32_e32 v239, 0xffff0000, v182
	v_lshlrev_b32_e32 v240, 16, v183
	v_and_b32_e32 v241, 0xffff0000, v183
	v_lshlrev_b32_e32 v242, 16, v184
	v_and_b32_e32 v243, 0xffff0000, v184
	v_lshlrev_b32_e32 v244, 16, v185
	v_and_b32_e32 v245, 0xffff0000, v185
	v_pk_add_f32 v[62:63], v[62:63], v[238:239]
	v_pk_add_f32 v[64:65], v[64:65], v[240:241]
	v_pk_add_f32 v[58:59], v[58:59], v[242:243]
	v_pk_add_f32 v[60:61], v[60:61], v[244:245]
	v_cvt_pk_bf16_f32 v182, v62, v63
	v_cvt_pk_bf16_f32 v183, v64, v65
	v_cvt_pk_bf16_f32 v184, v58, v59
	v_cvt_pk_bf16_f32 v185, v60, v61
	global_store_dwordx4 v[198:199], v[182:185], off
	v_pk_mul_f32 v[238:239], v[58:59], v[58:59]
	v_pk_mul_f32 v[240:241], v[60:61], v[60:61]
	v_pk_fma_f32 v[238:239], v[62:63], v[62:63], v[238:239]
	v_pk_fma_f32 v[240:241], v[64:65], v[64:65], v[240:241]
	s_nop 0
	v_add_f32_e32 v238, v238, v239
	v_add_f32_e32 v239, v240, v241
	v_add_f32_e32 v62, v238, v239
	s_waitcnt vmcnt(15)
	v_lshlrev_b32_e32 v238, 16, v186
	v_and_b32_e32 v239, 0xffff0000, v186
	v_lshlrev_b32_e32 v240, 16, v187
	v_and_b32_e32 v241, 0xffff0000, v187
	v_lshlrev_b32_e32 v242, 16, v188
	v_and_b32_e32 v243, 0xffff0000, v188
	v_lshlrev_b32_e32 v244, 16, v189
	v_and_b32_e32 v245, 0xffff0000, v189
	v_pk_add_f32 v[54:55], v[54:55], v[238:239]
	v_pk_add_f32 v[56:57], v[56:57], v[240:241]
	v_pk_add_f32 v[50:51], v[50:51], v[242:243]
	v_pk_add_f32 v[52:53], v[52:53], v[244:245]
	v_cvt_pk_bf16_f32 v186, v54, v55
	v_cvt_pk_bf16_f32 v187, v56, v57
	v_cvt_pk_bf16_f32 v188, v50, v51
	v_cvt_pk_bf16_f32 v189, v52, v53
	global_store_dwordx4 v[198:199], v[186:189], off offset:256
	v_pk_mul_f32 v[238:239], v[50:51], v[50:51]
	v_pk_mul_f32 v[240:241], v[52:53], v[52:53]
	v_pk_fma_f32 v[238:239], v[54:55], v[54:55], v[238:239]
	v_pk_fma_f32 v[240:241], v[56:57], v[56:57], v[240:241]
	s_nop 0
	v_add_f32_e32 v238, v238, v239
	v_add_f32_e32 v239, v240, v241
	v_add_f32_e32 v238, v238, v239
	v_add_f32_e32 v62, v62, v238
	v_lshl_add_u64 v[198:199], v[198:199], 0, s[22:23]
	s_waitcnt vmcnt(15)
; __device__ __forceinline__ unsigned cvt_pk_bf16(float lo, float hi) { f32x2_cv v = {lo, hi}; bf16x2_cv b = __builtin_convertvector(v, bf16x2_cv); return __builtin_bit_cast(unsigned, b); }
;     __device__ __forceinline__ void operator()(const f32x4 (&acc)[2][2][4][2], const Unit& u, int wr, int wc, int fr, int fq) const {
;     ...
; #pragma unroll
;             for (int m = 0; m < 4; ++m) {
;                 const int row = row0 + ai * HALF + m * 16; float ss = 0.f;
; #pragma unroll
;                 for (int bj = 0; bj < 2; ++bj) {
;                     const size_t off = (size_t)row * 1024 + col0 + bj * HALF;
;                     const u32x4 v = xv[m][bj];
;                     f32x4 x0 = {__uint_as_float(v.x << 16), __uint_as_float(v.x & 0xffff0000u), __uint_as_float(v.y << 16), __uint_as_float(v.y & 0xffff0000u)};
;                     f32x4 x1 = {__uint_as_float(v.z << 16), __uint_as_float(v.z & 0xffff0000u), __uint_as_float(v.w << 16), __uint_as_float(v.w & 0xffff0000u)};
;                     x0 = x0 + acc[ai][bj][m][0] * alpha; x1 = x1 + acc[ai][bj][m][1] * alpha;
;                     u32x4 w; w.x = cvt_pk_bf16(x0[0], x0[1]); w.y = cvt_pk_bf16(x0[2], x0[3]); w.z = cvt_pk_bf16(x1[0], x1[1]); w.w = cvt_pk_bf16(x1[2], x1[3]);
;                     *(u32x4*)(XB + off) = w;
;                     const f32x4 sq = x0 * x0 + x1 * x1;
;                     ss += (sq[0] + sq[1]) + (sq[2] + sq[3]);
	v_lshlrev_b32_e32 v238, 16, v190
	v_and_b32_e32 v239, 0xffff0000, v190
	v_lshlrev_b32_e32 v240, 16, v191
	v_and_b32_e32 v241, 0xffff0000, v191
	v_lshlrev_b32_e32 v242, 16, v192
	v_and_b32_e32 v243, 0xffff0000, v192
	v_lshlrev_b32_e32 v244, 16, v193
	v_and_b32_e32 v245, 0xffff0000, v193
	v_pk_add_f32 v[46:47], v[46:47], v[238:239]
	v_pk_add_f32 v[48:49], v[48:49], v[240:241]
	v_pk_add_f32 v[42:43], v[42:43], v[242:243]
	v_pk_add_f32 v[44:45], v[44:45], v[244:245]
	v_cvt_pk_bf16_f32 v190, v46, v47
	v_cvt_pk_bf16_f32 v191, v48, v49
	v_cvt_pk_bf16_f32 v192, v42, v43
	v_cvt_pk_bf16_f32 v193, v44, v45
	global_store_dwordx4 v[198:199], v[190:193], off
	v_pk_mul_f32 v[238:239], v[42:43], v[42:43]
	v_pk_mul_f32 v[240:241], v[44:45], v[44:45]
	v_pk_fma_f32 v[238:239], v[46:47], v[46:47], v[238:239]
	v_pk_fma_f32 v[240:241], v[48:49], v[48:49], v[240:241]
	s_nop 0
	v_add_f32_e32 v238, v238, v239
	v_add_f32_e32 v239, v240, v241
	v_add_f32_e32 v46, v238, v239
	s_waitcnt vmcnt(15)
	v_lshlrev_b32_e32 v238, 16, v194
	v_and_b32_e32 v239, 0xffff0000, v194
	v_lshlrev_b32_e32 v240, 16, v195
	v_and_b32_e32 v241, 0xffff0000, v195
	v_lshlrev_b32_e32 v242, 16, v196
	v_and_b32_e32 v243, 0xffff0000, v196
	v_lshlrev_b32_e32 v244, 16, v197
	v_and_b32_e32 v245, 0xffff0000, v197
	v_pk_add_f32 v[38:39], v[38:39], v[238:239]
	v_pk_add_f32 v[40:41], v[40:41], v[240:241]
	v_pk_add_f32 v[34:35], v[34:35], v[242:243]
	v_pk_add_f32 v[36:37], v[36:37], v[244:245]
	v_cvt_pk_bf16_f32 v194, v38, v39
	v_cvt_pk_bf16_f32 v195, v40, v41
	v_cvt_pk_bf16_f32 v196, v34, v35
	v_cvt_pk_bf16_f32 v197, v36, v37
	global_store_dwordx4 v[198:199], v[194:197], off offset:256
	v_pk_mul_f32 v[238:239], v[34:35], v[34:35]
	v_pk_mul_f32 v[240:241], v[36:37], v[36:37]
	v_pk_fma_f32 v[238:239], v[38:39], v[38:39], v[238:239]
	v_pk_fma_f32 v[240:241], v[40:41], v[40:41], v[240:241]
	s_nop 0
	v_add_f32_e32 v238, v238, v239
	v_add_f32_e32 v239, v240, v241
	v_add_f32_e32 v238, v238, v239
	v_add_f32_e32 v46, v46, v238
	v_lshl_add_u64 v[198:199], v[198:199], 0, s[22:23]
	s_waitcnt vmcnt(15)
	v_lshlrev_b32_e32 v238, 16, v222
	v_and_b32_e32 v239, 0xffff0000, v222
	v_lshlrev_b32_e32 v240, 16, v223
	v_and_b32_e32 v241, 0xffff0000, v223
	v_lshlrev_b32_e32 v242, 16, v224
	v_and_b32_e32 v243, 0xffff0000, v224
	v_lshlrev_b32_e32 v244, 16, v225
	v_and_b32_e32 v245, 0xffff0000, v225
	v_pk_add_f32 v[30:31], v[30:31], v[238:239]
	v_pk_add_f32 v[32:33], v[32:33], v[240:241]
	v_pk_add_f32 v[26:27], v[26:27], v[242:243]
	v_pk_add_f32 v[28:29], v[28:29], v[244:245]
	v_cvt_pk_bf16_f32 v222, v30, v31
	v_cvt_pk_bf16_f32 v223, v32, v33
	v_cvt_pk_bf16_f32 v224, v26, v27
	v_cvt_pk_bf16_f32 v225, v28, v29
	global_store_dwordx4 v[198:199], v[222:225], off
	v_pk_mul_f32 v[238:239], v[26:27], v[26:27]
	v_pk_mul_f32 v[240:241], v[28:29], v[28:29]
	v_pk_fma_f32 v[238:239], v[30:31], v[30:31], v[238:239]
	v_pk_fma_f32 v[240:241], v[32:33], v[32:33], v[240:241]
	s_nop 0
	v_add_f32_e32 v238, v238, v239
	v_add_f32_e32 v239, v240, v241
	v_add_f32_e32 v30, v238, v239
	s_waitcnt vmcnt(15)
	v_lshlrev_b32_e32 v238, 16, v226
	v_and_b32_e32 v239, 0xffff0000, v226
	v_lshlrev_b32_e32 v240, 16, v227
	v_and_b32_e32 v241, 0xffff0000, v227
	v_lshlrev_b32_e32 v242, 16, v228
	v_and_b32_e32 v243, 0xffff0000, v228
	v_lshlrev_b32_e32 v244, 16, v229
	v_and_b32_e32 v245, 0xffff0000, v229
	v_pk_add_f32 v[22:23], v[22:23], v[238:239]
	v_pk_add_f32 v[24:25], v[24:25], v[240:241]
	v_pk_add_f32 v[18:19], v[18:19], v[242:243]
	v_pk_add_f32 v[20:21], v[20:21], v[244:245]
	v_cvt_pk_bf16_f32 v226, v22, v23
	v_cvt_pk_bf16_f32 v227, v24, v25
	v_cvt_pk_bf16_f32 v228, v18, v19
	v_cvt_pk_bf16_f32 v229, v20, v21
	global_store_dwordx4 v[198:199], v[226:229], off offset:256
	v_pk_mul_f32 v[238:239], v[18:19], v[18:19]
	v_pk_mul_f32 v[240:241], v[20:21], v[20:21]
	v_pk_fma_f32 v[238:239], v[22:23], v[22:23], v[238:239]
	v_pk_fma_f32 v[240:241], v[24:25], v[24:25], v[240:241]
	s_nop 0
	v_add_f32_e32 v238, v238, v239
	v_add_f32_e32 v239, v240, v241
	v_add_f32_e32 v238, v238, v239
	v_add_f32_e32 v30, v30, v238
	v_lshl_add_u64 v[198:199], v[198:199], 0, s[22:23]
	s_waitcnt vmcnt(15)
;     __device__ __forceinline__ void operator()(const f32x4 (&acc)[2][2][4][2], const Unit& u, int wr, int wc, int fr, int fq) const {
;     ...
;                     const f32x4 sq = x0 * x0 + x1 * x1;
;                     ss += (sq[0] + sq[1]) + (sq[2] + sq[3]);
;                 }
;                 ss += __shfl_xor(ss, 16); ss += __shfl_xor(ss, 32);
;                 if (fq == 0) rsp_out[(size_t)row * 16 + u.pn * 4 + wc] = ss;
	v_lshlrev_b32_e32 v238, 16, v230
	v_and_b32_e32 v239, 0xffff0000, v230
	v_lshlrev_b32_e32 v240, 16, v231
	v_and_b32_e32 v241, 0xffff0000, v231
	v_lshlrev_b32_e32 v242, 16, v232
	v_and_b32_e32 v243, 0xffff0000, v232
	v_lshlrev_b32_e32 v244, 16, v233
	v_and_b32_e32 v245, 0xffff0000, v233
	v_pk_add_f32 v[14:15], v[14:15], v[238:239]
	v_pk_add_f32 v[16:17], v[16:17], v[240:241]
	v_pk_add_f32 v[10:11], v[10:11], v[242:243]
	v_pk_add_f32 v[12:13], v[12:13], v[244:245]
	v_cvt_pk_bf16_f32 v230, v14, v15
	v_cvt_pk_bf16_f32 v231, v16, v17
	v_cvt_pk_bf16_f32 v232, v10, v11
	v_cvt_pk_bf16_f32 v233, v12, v13
	global_store_dwordx4 v[198:199], v[230:233], off
	v_pk_mul_f32 v[238:239], v[10:11], v[10:11]
	v_pk_mul_f32 v[240:241], v[12:13], v[12:13]
	v_pk_fma_f32 v[238:239], v[14:15], v[14:15], v[238:239]
	v_pk_fma_f32 v[240:241], v[16:17], v[16:17], v[240:241]
	s_nop 0
	v_add_f32_e32 v238, v238, v239
	v_add_f32_e32 v239, v240, v241
	v_add_f32_e32 v14, v238, v239
	s_waitcnt vmcnt(15)
	v_lshlrev_b32_e32 v238, 16, v234
	v_and_b32_e32 v239, 0xffff0000, v234
	v_lshlrev_b32_e32 v240, 16, v235
	v_and_b32_e32 v241, 0xffff0000, v235
	v_lshlrev_b32_e32 v242, 16, v236
	v_and_b32_e32 v243, 0xffff0000, v236
	v_lshlrev_b32_e32 v244, 16, v237
	v_and_b32_e32 v245, 0xffff0000, v237
	v_pk_add_f32 v[6:7], v[6:7], v[238:239]
	v_pk_add_f32 v[8:9], v[8:9], v[240:241]
	v_pk_add_f32 v[2:3], v[2:3], v[242:243]
	v_pk_add_f32 v[4:5], v[4:5], v[244:245]
	v_cvt_pk_bf16_f32 v234, v6, v7
	v_cvt_pk_bf16_f32 v235, v8, v9
	v_cvt_pk_bf16_f32 v236, v2, v3
	v_cvt_pk_bf16_f32 v237, v4, v5
	global_store_dwordx4 v[198:199], v[234:237], off offset:256
	v_pk_mul_f32 v[238:239], v[2:3], v[2:3]
	v_pk_mul_f32 v[240:241], v[4:5], v[4:5]
	v_pk_fma_f32 v[238:239], v[6:7], v[6:7], v[238:239]
	v_pk_fma_f32 v[240:241], v[8:9], v[8:9], v[240:241]
	s_nop 0
	v_add_f32_e32 v238, v238, v239
	v_add_f32_e32 v239, v240, v241
	v_add_f32_e32 v238, v238, v239
	v_add_f32_e32 v14, v14, v238
	ds_bpermute_b32 v127, v215, v126
	ds_bpermute_b32 v111, v215, v110
	ds_bpermute_b32 v95, v215, v94
	ds_bpermute_b32 v79, v215, v78
	ds_bpermute_b32 v63, v215, v62
	ds_bpermute_b32 v47, v215, v46
	ds_bpermute_b32 v31, v215, v30
	ds_bpermute_b32 v15, v215, v14
	s_waitcnt lgkmcnt(0)
	v_add_f32_e32 v126, v126, v127
	v_add_f32_e32 v110, v110, v111
	v_add_f32_e32 v94, v94, v95
	v_add_f32_e32 v78, v78, v79
	v_add_f32_e32 v62, v62, v63
	v_add_f32_e32 v46, v46, v47
	v_add_f32_e32 v30, v30, v31
	v_add_f32_e32 v14, v14, v15
	ds_bpermute_b32 v127, v216, v126
	ds_bpermute_b32 v111, v216, v110
	ds_bpermute_b32 v95, v216, v94
	ds_bpermute_b32 v79, v216, v78
	ds_bpermute_b32 v63, v216, v62
	ds_bpermute_b32 v47, v216, v46
	ds_bpermute_b32 v31, v216, v30
	ds_bpermute_b32 v15, v216, v14
	s_waitcnt lgkmcnt(0)
	v_add_f32_e32 v126, v126, v127
	v_add_f32_e32 v110, v110, v111
	v_add_f32_e32 v94, v94, v95
	v_add_f32_e32 v78, v78, v79
	v_add_f32_e32 v62, v62, v63
	v_add_f32_e32 v46, v46, v47
	v_add_f32_e32 v30, v30, v31
	v_add_f32_e32 v14, v14, v15
	s_lshl_b32 s22, s9, 4
	s_lshl_b32 s88, s35, 2
	s_add_i32 s22, s22, s88
	v_lshlrev_b32_e32 v246, 6, v217
	v_mov_b32_e32 v247, 0
	v_lshl_add_u64 v[246:247], s[76:77], 0, v[246:247]
	v_lshl_add_u64 v[246:247], v[246:247], 0, s[22:23]
	s_mov_b32 s22, 0x2000
	v_lshl_add_u64 v[198:199], v[246:247], 0, s[22:23]
	s_and_saveexec_b64 s[24:25], s[4:5]
	global_store_dword v[246:247], v126, off
	global_store_dword v[246:247], v110, off offset:1024
	global_store_dword v[246:247], v94, off offset:2048
	global_store_dword v[246:247], v78, off offset:3072
	global_store_dword v[198:199], v62, off
	global_store_dword v[198:199], v46, off offset:1024
	global_store_dword v[198:199], v30, off offset:2048
	global_store_dword v[198:199], v14, off offset:3072
	s_or_b64 exec, exec, s[24:25]
	s_andn2_b64 vcc, exec, s[6:7]
	s_mov_b64 s[6:7], -1
	s_cbranch_vccnz .LBB0_34
	s_andn2_b64 vcc, exec, s[10:11]
	s_cbranch_vccnz .LBB0_33
	s_barrier
	s_branch .LBB0_33

; #define PG8_STAGE(bufoff, gbase, voff) do { _Pragma("unroll") for (int _i = 0; _i < 2; ++_i) \
;         __builtin_amdgcn_global_load_lds((const unsigned*)((const char*)(gbase) + (voff)[_i]), (PG8_LAS unsigned*)(lds + (bufoff) + ldsw + _i * 8192), 16, 0, 0); } while (0)
; #define PG8_LDA(dst, b, h) do { _Pragma("unroll") for (int m = 0; m < 4; ++m) _Pragma("unroll") for (int k = 0; k < 2; ++k) dst[m][k] = *(const PG8_LAS bf16x8*)(lds + PG8_SA(b, h) + aoff + m * 2048 + k * 1024); } while (0)
; #define PG8_LDB(dst, b, h) do { _Pragma("unroll") for (int n = 0; n < 2; ++n) _Pragma("unroll") for (int k = 0; k < 2; ++k) dst[n][k] = *(const PG8_LAS bf16x8*)(lds + PG8_SB(b, h) + boff + n * 2048 + k * 1024); } while (0)
; #define PG8_MMA(ai, bj, At, Bt) do { __builtin_amdgcn_s_setprio(1); _Pragma("unroll") for (int m = 0; m < 4; ++m) _Pragma("unroll") for (int n = 0; n < 2; ++n) _Pragma("unroll") for (int k = 0; k < 2; ++k) \
;         acc[ai][bj][m][n] = __builtin_amdgcn_mfma_f32_16x16x32_bf16(Bt[n][k], At[m][k], acc[ai][bj][m][n], 0, 0, 0); __builtin_amdgcn_s_setprio(0); } while (0)
; #define PG8_WAIT_V(n) asm volatile("s_waitcnt vmcnt(" #n ")" ::: "memory")
; #define PG8_WAIT_L(n) asm volatile("s_waitcnt lgkmcnt(" #n ")" ::: "memory")
; #define PG8_BAR __builtin_amdgcn_s_barrier()
; #define PG8_SCHED __builtin_amdgcn_sched_barrier(0)
; template <class Epi, class Sched, bool ALIGN_EPI = false, bool SP2 = false>
; __device__ __forceinline__ void gemm_phase(PG8_LAS unsigned char* lds, const Gemm g, const Sched& S, const Epi& E) {
;     ...
;             PG8_LDB(B0, 0, 0); PG8_LDB(B1, 0, 1); PG8_SCHED; PG8_LDA(At, 0, 0); PG8_STAGE(PG8_SA(1, 1), a1 + hstep, voffA);
;             PG8_WAIT_V(8); PG8_WAIT_L(0); PG8_BAR; PG8_MMA(0, 0, At, B0); PG8_MMA(0, 1, At, B1); PG8_BAR; PG8_SCHED;
;             PG8_LDA(At, 0, 1); PG8_STAGE(PG8_SB(0, 0), b2, voffB); PG8_STAGE(PG8_SB(0, 1), b2 + hstep, voffB); PG8_STAGE(PG8_SA(0, 0), a2, voffA);
;             PG8_WAIT_V(8); PG8_WAIT_L(0); PG8_BAR; PG8_MMA(1, 0, At, B0); PG8_MMA(1, 1, At, B1); PG8_BAR; PG8_SCHED;
.LBB0_459:
	s_add_u32 s20, s18, 0x100
	s_addc_u32 s21, s19, 0
	s_add_i32 s50, 0, 0x10000
	s_cmp_eq_u32 s49, 40
	s_cselect_b32 s25, s9, s21
	s_cselect_b32 s24, s8, s20
	s_cselect_b32 s23, s17, s48
	s_cselect_b32 s22, s16, s47
	s_add_i32 s51, 0, 0x14000
	v_add_u32_e32 v142, s50, v165
	v_add_u32_e32 v182, s51, v165
	ds_read_b128 v[130:133], v142
	ds_read_b128 v[134:137], v142 offset:1024
	ds_read_b128 v[138:141], v142 offset:2048
	ds_read_b128 v[142:145], v142 offset:3072
	ds_read_b128 v[146:149], v182
	ds_read_b128 v[150:153], v182 offset:1024
	ds_read_b128 v[154:157], v182 offset:2048
	ds_read_b128 v[182:185], v182 offset:3072
	v_lshl_add_u64 v[198:199], s[18:19], 0, v[178:179]
	s_add_i32 m0, s28, 0xc000
	ds_read_b128 v[186:189], v214
	ds_read_b128 v[190:193], v214 offset:1024
	ds_read_b128 v[194:197], v214 offset:2048
	ds_read_b128 v[216:219], v214 offset:3072
	ds_read_b128 v[220:223], v214 offset:4096
	ds_read_b128 v[224:227], v214 offset:5120
	ds_read_b128 v[228:231], v214 offset:6144
	ds_read_b128 v[232:235], v214 offset:7168
	global_load_lds_dwordx4 v[198:199], off
	v_lshl_add_u64 v[198:199], s[18:19], 0, v[180:181]
	s_add_i32 m0, s28, 0xe000
	s_nop 0
	global_load_lds_dwordx4 v[198:199], off
	s_waitcnt vmcnt(8)
	s_waitcnt lgkmcnt(0)
	s_barrier
	s_setprio 1
	s_waitcnt lgkmcnt(0)
	v_mfma_f32_16x16x32_bf16 v[126:129], v[130:133], v[186:189], v[126:129]
	v_mfma_f32_16x16x32_bf16 v[122:125], v[138:141], v[186:189], v[122:125]
	v_mfma_f32_16x16x32_bf16 v[110:113], v[130:133], v[194:197], v[110:113]
	v_mfma_f32_16x16x32_bf16 v[106:109], v[138:141], v[194:197], v[106:109]
	v_mfma_f32_16x16x32_bf16 v[94:97], v[130:133], v[220:223], v[94:97]
	v_mfma_f32_16x16x32_bf16 v[90:93], v[138:141], v[220:223], v[90:93]
	v_mfma_f32_16x16x32_bf16 v[78:81], v[130:133], v[228:231], v[78:81]
	v_mfma_f32_16x16x32_bf16 v[74:77], v[138:141], v[228:231], v[74:77]
	v_mfma_f32_16x16x32_bf16 v[126:129], v[134:137], v[190:193], v[126:129]
	v_mfma_f32_16x16x32_bf16 v[122:125], v[142:145], v[190:193], v[122:125]
	v_mfma_f32_16x16x32_bf16 v[110:113], v[134:137], v[216:219], v[110:113]
	v_mfma_f32_16x16x32_bf16 v[106:109], v[142:145], v[216:219], v[106:109]
	v_mfma_f32_16x16x32_bf16 v[94:97], v[134:137], v[224:227], v[94:97]
	v_mfma_f32_16x16x32_bf16 v[90:93], v[142:145], v[224:227], v[90:93]
	v_mfma_f32_16x16x32_bf16 v[78:81], v[134:137], v[232:235], v[78:81]
	v_mfma_f32_16x16x32_bf16 v[74:77], v[142:145], v[232:235], v[74:77]
	s_setprio 0
	s_setprio 1
	v_mfma_f32_16x16x32_bf16 v[118:121], v[146:149], v[186:189], v[118:121]
	v_mfma_f32_16x16x32_bf16 v[114:117], v[154:157], v[186:189], v[114:117]
	v_mfma_f32_16x16x32_bf16 v[102:105], v[146:149], v[194:197], v[102:105]
	v_mfma_f32_16x16x32_bf16 v[98:101], v[154:157], v[194:197], v[98:101]
	v_mfma_f32_16x16x32_bf16 v[86:89], v[146:149], v[220:223], v[86:89]
	v_mfma_f32_16x16x32_bf16 v[82:85], v[154:157], v[220:223], v[82:85]
	v_mfma_f32_16x16x32_bf16 v[70:73], v[146:149], v[228:231], v[70:73]
	v_mfma_f32_16x16x32_bf16 v[66:69], v[154:157], v[228:231], v[66:69]
	v_mfma_f32_16x16x32_bf16 v[118:121], v[150:153], v[190:193], v[118:121]
	v_mfma_f32_16x16x32_bf16 v[114:117], v[182:185], v[190:193], v[114:117]
	v_mfma_f32_16x16x32_bf16 v[102:105], v[150:153], v[216:219], v[102:105]
	v_mfma_f32_16x16x32_bf16 v[98:101], v[182:185], v[216:219], v[98:101]
	v_mfma_f32_16x16x32_bf16 v[86:89], v[150:153], v[224:227], v[86:89]
	v_mfma_f32_16x16x32_bf16 v[82:85], v[182:185], v[224:227], v[82:85]
	v_mfma_f32_16x16x32_bf16 v[70:73], v[150:153], v[232:235], v[70:73]
	v_mfma_f32_16x16x32_bf16 v[66:69], v[182:185], v[232:235], v[66:69]
	s_setprio 0
	s_barrier
	s_add_i32 s18, s50, s2
	v_lshl_add_u64 v[198:199], s[22:23], 0, v[0:1]
	s_mov_b32 m0, s18
	ds_read_b128 v[186:189], v214 offset:16384
	ds_read_b128 v[190:193], v214 offset:17408
	ds_read_b128 v[194:197], v214 offset:18432
	ds_read_b128 v[216:219], v214 offset:19456
	ds_read_b128 v[220:223], v214 offset:20480
	ds_read_b128 v[224:227], v214 offset:21504
	ds_read_b128 v[228:231], v214 offset:22528
	ds_read_b128 v[232:235], v214 offset:23552
	global_load_lds_dwordx4 v[198:199], off
	s_add_i32 m0, s18, 0x2000
	s_add_u32 s18, s22, 0xb0000
	v_lshl_add_u64 v[236:237], s[22:23], 0, v[172:173]
	s_addc_u32 s19, s23, 0
	s_add_i32 s50, s51, s2
	global_load_lds_dwordx4 v[236:237], off
	v_lshl_add_u64 v[238:239], s[18:19], 0, v[0:1]
	s_mov_b32 m0, s50
	v_lshl_add_u64 v[240:241], s[24:25], 0, v[174:175]
	global_load_lds_dwordx4 v[238:239], off
	v_lshl_add_u64 v[238:239], s[18:19], 0, v[172:173]
	s_add_i32 m0, s50, 0x2000
	s_nop 0
	global_load_lds_dwordx4 v[238:239], off
	v_lshl_add_u64 v[238:239], s[24:25], 0, v[176:177]
	s_mov_b32 m0, s28
	s_nop 0
	global_load_lds_dwordx4 v[238:239], off
	s_mov_b32 m0, s29
	s_nop 0
	global_load_lds_dwordx4 v[240:241], off
	s_waitcnt vmcnt(8)
	s_waitcnt lgkmcnt(0)
	s_barrier
; #define PG8_STAGE(bufoff, gbase, voff) do { _Pragma("unroll") for (int _i = 0; _i < 2; ++_i) \
;         __builtin_amdgcn_global_load_lds((const unsigned*)((const char*)(gbase) + (voff)[_i]), (PG8_LAS unsigned*)(lds + (bufoff) + ldsw + _i * 8192), 16, 0, 0); } while (0)
; #define PG8_LDA(dst, b, h) do { _Pragma("unroll") for (int m = 0; m < 4; ++m) _Pragma("unroll") for (int k = 0; k < 2; ++k) dst[m][k] = *(const PG8_LAS bf16x8*)(lds + PG8_SA(b, h) + aoff + m * 2048 + k * 1024); } while (0)
; #define PG8_LDB(dst, b, h) do { _Pragma("unroll") for (int n = 0; n < 2; ++n) _Pragma("unroll") for (int k = 0; k < 2; ++k) dst[n][k] = *(const PG8_LAS bf16x8*)(lds + PG8_SB(b, h) + boff + n * 2048 + k * 1024); } while (0)
; #define PG8_MMA(ai, bj, At, Bt) do { __builtin_amdgcn_s_setprio(1); _Pragma("unroll") for (int m = 0; m < 4; ++m) _Pragma("unroll") for (int n = 0; n < 2; ++n) _Pragma("unroll") for (int k = 0; k < 2; ++k) \
;         acc[ai][bj][m][n] = __builtin_amdgcn_mfma_f32_16x16x32_bf16(Bt[n][k], At[m][k], acc[ai][bj][m][n], 0, 0, 0); __builtin_amdgcn_s_setprio(0); } while (0)
; #define PG8_WAIT_V(n) asm volatile("s_waitcnt vmcnt(" #n ")" ::: "memory")
; #define PG8_WAIT_L(n) asm volatile("s_waitcnt lgkmcnt(" #n ")" ::: "memory")
; #define PG8_BAR __builtin_amdgcn_s_barrier()
; #define PG8_SCHED __builtin_amdgcn_sched_barrier(0)
; template <class Epi, class Sched, bool ALIGN_EPI = false, bool SP2 = false>
; __device__ __forceinline__ void gemm_phase(PG8_LAS unsigned char* lds, const Gemm g, const Sched& S, const Epi& E) {
;     ...
;             PG8_WAIT_V(8); PG8_WAIT_L(0); PG8_BAR; PG8_MMA(1, 0, At, B0); PG8_MMA(1, 1, At, B1); PG8_BAR; PG8_SCHED;
;             PG8_LDB(B0, 1, 0); PG8_LDB(B1, 1, 1); PG8_SCHED; PG8_LDA(At, 1, 0); PG8_STAGE(PG8_SA(0, 1), a2 + hstep, voffA);
;             PG8_WAIT_V(8); PG8_WAIT_L(0); PG8_BAR; PG8_MMA(0, 0, At, B0); PG8_MMA(0, 1, At, B1); PG8_BAR; PG8_SCHED;
	s_setprio 1
	s_waitcnt lgkmcnt(0)
	v_mfma_f32_16x16x32_bf16 v[62:65], v[130:133], v[186:189], v[62:65]
	v_mfma_f32_16x16x32_bf16 v[58:61], v[138:141], v[186:189], v[58:61]
	v_mfma_f32_16x16x32_bf16 v[46:49], v[130:133], v[194:197], v[46:49]
	v_mfma_f32_16x16x32_bf16 v[42:45], v[138:141], v[194:197], v[42:45]
	v_mfma_f32_16x16x32_bf16 v[30:33], v[130:133], v[220:223], v[30:33]
	v_mfma_f32_16x16x32_bf16 v[26:29], v[138:141], v[220:223], v[26:29]
	v_mfma_f32_16x16x32_bf16 v[14:17], v[130:133], v[228:231], v[14:17]
	v_mfma_f32_16x16x32_bf16 v[10:13], v[138:141], v[228:231], v[10:13]
	v_mfma_f32_16x16x32_bf16 v[62:65], v[134:137], v[190:193], v[62:65]
	v_mfma_f32_16x16x32_bf16 v[58:61], v[142:145], v[190:193], v[58:61]
	v_mfma_f32_16x16x32_bf16 v[46:49], v[134:137], v[216:219], v[46:49]
	v_mfma_f32_16x16x32_bf16 v[42:45], v[142:145], v[216:219], v[42:45]
	v_mfma_f32_16x16x32_bf16 v[30:33], v[134:137], v[224:227], v[30:33]
	v_mfma_f32_16x16x32_bf16 v[26:29], v[142:145], v[224:227], v[26:29]
	v_mfma_f32_16x16x32_bf16 v[14:17], v[134:137], v[232:235], v[14:17]
	v_mfma_f32_16x16x32_bf16 v[10:13], v[142:145], v[232:235], v[10:13]
	s_setprio 0
	s_setprio 1
	v_mfma_f32_16x16x32_bf16 v[54:57], v[146:149], v[186:189], v[54:57]
	v_mfma_f32_16x16x32_bf16 v[50:53], v[154:157], v[186:189], v[50:53]
	v_mfma_f32_16x16x32_bf16 v[38:41], v[146:149], v[194:197], v[38:41]
	v_mfma_f32_16x16x32_bf16 v[34:37], v[154:157], v[194:197], v[34:37]
	v_mfma_f32_16x16x32_bf16 v[22:25], v[146:149], v[220:223], v[22:25]
	v_mfma_f32_16x16x32_bf16 v[18:21], v[154:157], v[220:223], v[18:21]
	v_mfma_f32_16x16x32_bf16 v[6:9], v[146:149], v[228:231], v[6:9]
	v_mfma_f32_16x16x32_bf16 v[2:5], v[154:157], v[228:231], v[2:5]
	v_mfma_f32_16x16x32_bf16 v[54:57], v[150:153], v[190:193], v[54:57]
	v_mfma_f32_16x16x32_bf16 v[50:53], v[182:185], v[190:193], v[50:53]
	v_mfma_f32_16x16x32_bf16 v[38:41], v[150:153], v[216:219], v[38:41]
	v_mfma_f32_16x16x32_bf16 v[34:37], v[182:185], v[216:219], v[34:37]
	v_mfma_f32_16x16x32_bf16 v[22:25], v[150:153], v[224:227], v[22:25]
	v_mfma_f32_16x16x32_bf16 v[18:21], v[182:185], v[224:227], v[18:21]
	v_mfma_f32_16x16x32_bf16 v[6:9], v[150:153], v[232:235], v[6:9]
	v_mfma_f32_16x16x32_bf16 v[2:5], v[182:185], v[232:235], v[2:5]
	s_setprio 0
	s_barrier
	s_add_i32 s50, 0, 0x18000
	s_add_i32 s51, 0, 0x1c000
	v_add_u32_e32 v142, s50, v165
	v_add_u32_e32 v182, s51, v165
	ds_read_b128 v[130:133], v142
	ds_read_b128 v[134:137], v142 offset:1024
	ds_read_b128 v[138:141], v142 offset:2048
	ds_read_b128 v[142:145], v142 offset:3072
	ds_read_b128 v[146:149], v182
	ds_read_b128 v[150:153], v182 offset:1024
	ds_read_b128 v[154:157], v182 offset:2048
	ds_read_b128 v[182:185], v182 offset:3072
	s_add_u32 s18, s24, 0xb0000
	s_addc_u32 s19, s25, 0
	s_mov_b32 m0, s30
	v_lshl_add_u64 v[242:243], s[18:19], 0, v[176:177]
	ds_read_b128 v[186:189], v214 offset:32768
	ds_read_b128 v[190:193], v214 offset:33792
	ds_read_b128 v[194:197], v214 offset:34816
	ds_read_b128 v[216:219], v214 offset:35840
	ds_read_b128 v[220:223], v214 offset:36864
	ds_read_b128 v[224:227], v214 offset:37888
	ds_read_b128 v[228:231], v214 offset:38912
	ds_read_b128 v[232:235], v214 offset:39936
	global_load_lds_dwordx4 v[242:243], off
	v_lshl_add_u64 v[242:243], s[18:19], 0, v[174:175]
	s_mov_b32 m0, s31
	s_nop 0
	global_load_lds_dwordx4 v[242:243], off
	s_waitcnt vmcnt(8)
	s_waitcnt lgkmcnt(0)
	s_barrier
	s_setprio 1
	s_waitcnt lgkmcnt(0)
	v_mfma_f32_16x16x32_bf16 v[126:129], v[130:133], v[186:189], v[126:129]
	v_mfma_f32_16x16x32_bf16 v[122:125], v[138:141], v[186:189], v[122:125]
	v_mfma_f32_16x16x32_bf16 v[110:113], v[130:133], v[194:197], v[110:113]
	v_mfma_f32_16x16x32_bf16 v[106:109], v[138:141], v[194:197], v[106:109]
	v_mfma_f32_16x16x32_bf16 v[94:97], v[130:133], v[220:223], v[94:97]
	v_mfma_f32_16x16x32_bf16 v[90:93], v[138:141], v[220:223], v[90:93]
	v_mfma_f32_16x16x32_bf16 v[78:81], v[130:133], v[228:231], v[78:81]
	v_mfma_f32_16x16x32_bf16 v[74:77], v[138:141], v[228:231], v[74:77]
	v_mfma_f32_16x16x32_bf16 v[126:129], v[134:137], v[190:193], v[126:129]
	v_mfma_f32_16x16x32_bf16 v[122:125], v[142:145], v[190:193], v[122:125]
	v_mfma_f32_16x16x32_bf16 v[110:113], v[134:137], v[216:219], v[110:113]
	v_mfma_f32_16x16x32_bf16 v[106:109], v[142:145], v[216:219], v[106:109]
	v_mfma_f32_16x16x32_bf16 v[94:97], v[134:137], v[224:227], v[94:97]
	v_mfma_f32_16x16x32_bf16 v[90:93], v[142:145], v[224:227], v[90:93]
	v_mfma_f32_16x16x32_bf16 v[78:81], v[134:137], v[232:235], v[78:81]
	v_mfma_f32_16x16x32_bf16 v[74:77], v[142:145], v[232:235], v[74:77]
	s_setprio 0
	s_setprio 1
	v_mfma_f32_16x16x32_bf16 v[118:121], v[146:149], v[186:189], v[118:121]
	v_mfma_f32_16x16x32_bf16 v[114:117], v[154:157], v[186:189], v[114:117]
	v_mfma_f32_16x16x32_bf16 v[102:105], v[146:149], v[194:197], v[102:105]
	v_mfma_f32_16x16x32_bf16 v[98:101], v[154:157], v[194:197], v[98:101]
	v_mfma_f32_16x16x32_bf16 v[86:89], v[146:149], v[220:223], v[86:89]
	v_mfma_f32_16x16x32_bf16 v[82:85], v[154:157], v[220:223], v[82:85]
	v_mfma_f32_16x16x32_bf16 v[70:73], v[146:149], v[228:231], v[70:73]
	v_mfma_f32_16x16x32_bf16 v[66:69], v[154:157], v[228:231], v[66:69]
	v_mfma_f32_16x16x32_bf16 v[118:121], v[150:153], v[190:193], v[118:121]
	v_mfma_f32_16x16x32_bf16 v[114:117], v[182:185], v[190:193], v[114:117]
	v_mfma_f32_16x16x32_bf16 v[102:105], v[150:153], v[216:219], v[102:105]
	v_mfma_f32_16x16x32_bf16 v[98:101], v[182:185], v[216:219], v[98:101]
	v_mfma_f32_16x16x32_bf16 v[86:89], v[150:153], v[224:227], v[86:89]
	v_mfma_f32_16x16x32_bf16 v[82:85], v[182:185], v[224:227], v[82:85]
	v_mfma_f32_16x16x32_bf16 v[70:73], v[150:153], v[232:235], v[70:73]
	v_mfma_f32_16x16x32_bf16 v[66:69], v[182:185], v[232:235], v[66:69]
	s_setprio 0
	s_barrier
; #define PG8_STAGE(bufoff, gbase, voff) do { _Pragma("unroll") for (int _i = 0; _i < 2; ++_i) \
;         __builtin_amdgcn_global_load_lds((const unsigned*)((const char*)(gbase) + (voff)[_i]), (PG8_LAS unsigned*)(lds + (bufoff) + ldsw + _i * 8192), 16, 0, 0); } while (0)
; #define PG8_LDA(dst, b, h) do { _Pragma("unroll") for (int m = 0; m < 4; ++m) _Pragma("unroll") for (int k = 0; k < 2; ++k) dst[m][k] = *(const PG8_LAS bf16x8*)(lds + PG8_SA(b, h) + aoff + m * 2048 + k * 1024); } while (0)
; #define PG8_MMA(ai, bj, At, Bt) do { __builtin_amdgcn_s_setprio(1); _Pragma("unroll") for (int m = 0; m < 4; ++m) _Pragma("unroll") for (int n = 0; n < 2; ++n) _Pragma("unroll") for (int k = 0; k < 2; ++k) \
;         acc[ai][bj][m][n] = __builtin_amdgcn_mfma_f32_16x16x32_bf16(Bt[n][k], At[m][k], acc[ai][bj][m][n], 0, 0, 0); __builtin_amdgcn_s_setprio(0); } while (0)
; #define PG8_WAIT_V(n) asm volatile("s_waitcnt vmcnt(" #n ")" ::: "memory")
; #define PG8_WAIT_L(n) asm volatile("s_waitcnt lgkmcnt(" #n ")" ::: "memory")
; #define PG8_BAR __builtin_amdgcn_s_barrier()
; #define PG8_SCHED __builtin_amdgcn_sched_barrier(0)
; template <class Epi, class Sched, bool ALIGN_EPI = false, bool SP2 = false>
; __device__ __forceinline__ void gemm_phase(PG8_LAS unsigned char* lds, const Gemm g, const Sched& S, const Epi& E) {
;     ...
;             PG8_LDA(At, 1, 1); PG8_STAGE(PG8_SB(1, 0), b3, voffB); PG8_STAGE(PG8_SB(1, 1), b3 + hstep, voffB); PG8_STAGE(PG8_SA(1, 0), a3, voffA);
;             PG8_WAIT_V(8); PG8_WAIT_L(0); PG8_BAR; PG8_MMA(1, 0, At, B0); PG8_MMA(1, 1, At, B1); PG8_BAR; PG8_SCHED;
;     __device__ __forceinline__ void operator()(const f32x4 (&acc)[2][2][4][2], const Unit& u, int wr, int wc, int fr, int fq) const {
;         const int row0 = u.pm * BM + wr * 64 + fr, col0 = u.pn * BM + wc * 32 + 8 * fq;
; #pragma unroll
;         for (int ai = 0; ai < 2; ++ai) {
;             u32x4 xv[4][2];
; #pragma unroll
;             for (int m = 0; m < 4; ++m)
; #pragma unroll
;                 for (int bj = 0; bj < 2; ++bj) xv[m][bj] = *(const u32x4*)(XB + (size_t)(row0 + ai * HALF + m * 16) * 1024 + col0 + bj * HALF);
;             asm volatile("" ::: "memory");
	s_add_i32 s18, s50, s2
	v_lshl_add_u64 v[198:199], v[198:199], 0, s[90:91]
	s_mov_b32 m0, s18
	ds_read_b128 v[186:189], v214 offset:49152
	ds_read_b128 v[190:193], v214 offset:50176
	ds_read_b128 v[194:197], v214 offset:51200
	ds_read_b128 v[216:219], v214 offset:52224
	ds_read_b128 v[220:223], v214 offset:53248
	ds_read_b128 v[224:227], v214 offset:54272
	ds_read_b128 v[228:231], v214 offset:55296
	ds_read_b128 v[232:235], v214 offset:56320
	global_load_lds_dwordx4 v[198:199], off
	s_add_i32 m0, s18, 0x2000
	s_add_u32 s18, s22, 0xb0080
	v_lshl_add_u64 v[198:199], v[236:237], 0, s[90:91]
	s_addc_u32 s19, s23, 0
	s_add_i32 s22, s51, s2
	global_load_lds_dwordx4 v[198:199], off
	v_lshl_add_u64 v[198:199], s[18:19], 0, v[0:1]
	s_mov_b32 m0, s22
	s_nop 0
	global_load_lds_dwordx4 v[198:199], off
	v_lshl_add_u64 v[198:199], s[18:19], 0, v[172:173]
	s_add_i32 m0, s22, 0x2000
	s_nop 0
	global_load_lds_dwordx4 v[198:199], off
	v_lshl_add_u64 v[198:199], v[238:239], 0, s[90:91]
	s_mov_b32 m0, s35
	s_nop 0
	global_load_lds_dwordx4 v[198:199], off
	v_lshl_add_u64 v[198:199], v[240:241], 0, s[90:91]
	s_mov_b32 m0, s37
	s_nop 0
	global_load_lds_dwordx4 v[198:199], off
	s_waitcnt vmcnt(8)
	s_waitcnt lgkmcnt(0)
	s_barrier
	s_setprio 1
	s_waitcnt lgkmcnt(0)
	v_mfma_f32_16x16x32_bf16 v[62:65], v[130:133], v[186:189], v[62:65]
	v_mfma_f32_16x16x32_bf16 v[58:61], v[138:141], v[186:189], v[58:61]
	v_mfma_f32_16x16x32_bf16 v[46:49], v[130:133], v[194:197], v[46:49]
	v_mfma_f32_16x16x32_bf16 v[42:45], v[138:141], v[194:197], v[42:45]
	v_mfma_f32_16x16x32_bf16 v[30:33], v[130:133], v[220:223], v[30:33]
	v_mfma_f32_16x16x32_bf16 v[26:29], v[138:141], v[220:223], v[26:29]
	v_mfma_f32_16x16x32_bf16 v[14:17], v[130:133], v[228:231], v[14:17]
	v_mfma_f32_16x16x32_bf16 v[10:13], v[138:141], v[228:231], v[10:13]
	v_mfma_f32_16x16x32_bf16 v[62:65], v[134:137], v[190:193], v[62:65]
	v_mfma_f32_16x16x32_bf16 v[58:61], v[142:145], v[190:193], v[58:61]
	v_mfma_f32_16x16x32_bf16 v[46:49], v[134:137], v[216:219], v[46:49]
	v_mfma_f32_16x16x32_bf16 v[42:45], v[142:145], v[216:219], v[42:45]
	v_mfma_f32_16x16x32_bf16 v[30:33], v[134:137], v[224:227], v[30:33]
	v_mfma_f32_16x16x32_bf16 v[26:29], v[142:145], v[224:227], v[26:29]
	v_mfma_f32_16x16x32_bf16 v[14:17], v[134:137], v[232:235], v[14:17]
	v_mfma_f32_16x16x32_bf16 v[10:13], v[142:145], v[232:235], v[10:13]
	s_setprio 0
	s_setprio 1
	v_mfma_f32_16x16x32_bf16 v[54:57], v[146:149], v[186:189], v[54:57]
	v_mfma_f32_16x16x32_bf16 v[50:53], v[154:157], v[186:189], v[50:53]
	v_mfma_f32_16x16x32_bf16 v[38:41], v[146:149], v[194:197], v[38:41]
	v_mfma_f32_16x16x32_bf16 v[34:37], v[154:157], v[194:197], v[34:37]
	v_mfma_f32_16x16x32_bf16 v[22:25], v[146:149], v[220:223], v[22:25]
	v_mfma_f32_16x16x32_bf16 v[18:21], v[154:157], v[220:223], v[18:21]
	v_mfma_f32_16x16x32_bf16 v[6:9], v[146:149], v[228:231], v[6:9]
	v_mfma_f32_16x16x32_bf16 v[2:5], v[154:157], v[228:231], v[2:5]
	v_mfma_f32_16x16x32_bf16 v[54:57], v[150:153], v[190:193], v[54:57]
	v_mfma_f32_16x16x32_bf16 v[50:53], v[182:185], v[190:193], v[50:53]
	v_mfma_f32_16x16x32_bf16 v[38:41], v[150:153], v[216:219], v[38:41]
	v_mfma_f32_16x16x32_bf16 v[34:37], v[182:185], v[216:219], v[34:37]
	v_mfma_f32_16x16x32_bf16 v[22:25], v[150:153], v[224:227], v[22:25]
	v_mfma_f32_16x16x32_bf16 v[18:21], v[182:185], v[224:227], v[18:21]
	v_mfma_f32_16x16x32_bf16 v[6:9], v[150:153], v[232:235], v[6:9]
	v_mfma_f32_16x16x32_bf16 v[2:5], v[182:185], v[232:235], v[2:5]
	s_setprio 0
	s_barrier
	s_add_i32 s49, s49, 2
	s_add_u32 s47, s47, 0x100
	s_addc_u32 s48, s48, 0
	s_cmp_gt_u32 s49, 41
	s_mov_b64 s[18:19], s[20:21]
	s_cbranch_scc0 .LBB0_459
	v_lshl_or_b32 v198, s45, 8, v213
	v_lshl_add_u32 v217, s46, 8, v158
	v_lshlrev_b32_e32 v246, 1, v198
	v_lshl_add_u32 v246, v217, 11, v246
	v_mov_b32_e32 v247, 0
	s_mov_b32 s18, 0x8000
	s_mov_b32 s19, 0
	s_mov_b32 s88, 0x28000
	v_lshl_add_u64 v[246:247], s[94:95], 0, v[246:247]
	v_xor_b32_e32 v215, 16, v201
	v_xor_b32_e32 v216, 32, v201
	v_mov_b32_e32 v198, v246
	v_mov_b32_e32 v199, v247
	global_load_dwordx4 v[130:133], v[246:247], off
	global_load_dwordx4 v[134:137], v[246:247], off offset:256
	v_lshl_add_u64 v[246:247], v[246:247], 0, s[18:19]
	global_load_dwordx4 v[138:141], v[246:247], off
	global_load_dwordx4 v[142:145], v[246:247], off offset:256
	v_lshl_add_u64 v[246:247], v[246:247], 0, s[18:19]
	global_load_dwordx4 v[146:149], v[246:247], off
	global_load_dwordx4 v[150:153], v[246:247], off offset:256
	v_lshl_add_u64 v[246:247], v[246:247], 0, s[18:19]
	global_load_dwordx4 v[154:157], v[246:247], off
	global_load_dwordx4 v[218:221], v[246:247], off offset:256
	v_lshl_add_u64 v[246:247], v[246:247], 0, s[88:89]
	global_load_dwordx4 v[182:185], v[246:247], off
	global_load_dwordx4 v[186:189], v[246:247], off offset:256
	v_lshl_add_u64 v[246:247], v[246:247], 0, s[18:19]
	global_load_dwordx4 v[190:193], v[246:247], off
	global_load_dwordx4 v[194:197], v[246:247], off offset:256
	v_lshl_add_u64 v[246:247], v[246:247], 0, s[18:19]
	global_load_dwordx4 v[222:225], v[246:247], off
	global_load_dwordx4 v[226:229], v[246:247], off offset:256
	v_lshl_add_u64 v[246:247], v[246:247], 0, s[18:19]
	global_load_dwordx4 v[230:233], v[246:247], off
	global_load_dwordx4 v[234:237], v[246:247], off offset:256
	v_lshlrev_b32_e32 v215, 2, v215
	v_lshlrev_b32_e32 v216, 2, v216
	s_and_b64 vcc, exec, s[14:15]
	s_cbranch_vccz .LBB0_462
	s_barrier
; __device__ __forceinline__ unsigned cvt_pk_bf16(float lo, float hi) { f32x2_cv v = {lo, hi}; bf16x2_cv b = __builtin_convertvector(v, bf16x2_cv); return __builtin_bit_cast(unsigned, b); }
;     __device__ __forceinline__ void operator()(const f32x4 (&acc)[2][2][4][2], const Unit& u, int wr, int wc, int fr, int fq) const {
;     ...
;                 for (int bj = 0; bj < 2; ++bj) xv[m][bj] = *(const u32x4*)(XB + (size_t)(row0 + ai * HALF + m * 16) * 1024 + col0 + bj * HALF);
;             asm volatile("" ::: "memory");
; #pragma unroll
;             for (int m = 0; m < 4; ++m) {
;                 const int row = row0 + ai * HALF + m * 16; float ss = 0.f;
; #pragma unroll
;                 for (int bj = 0; bj < 2; ++bj) {
;                     const size_t off = (size_t)row * 1024 + col0 + bj * HALF;
;                     const u32x4 v = xv[m][bj];
;                     f32x4 x0 = {__uint_as_float(v.x << 16), __uint_as_float(v.x & 0xffff0000u), __uint_as_float(v.y << 16), __uint_as_float(v.y & 0xffff0000u)};
;                     f32x4 x1 = {__uint_as_float(v.z << 16), __uint_as_float(v.z & 0xffff0000u), __uint_as_float(v.w << 16), __uint_as_float(v.w & 0xffff0000u)};
;                     x0 = x0 + acc[ai][bj][m][0] * alpha; x1 = x1 + acc[ai][bj][m][1] * alpha;
;                     u32x4 w; w.x = cvt_pk_bf16(x0[0], x0[1]); w.y = cvt_pk_bf16(x0[2], x0[3]); w.z = cvt_pk_bf16(x1[0], x1[1]); w.w = cvt_pk_bf16(x1[2], x1[3]);
;                     *(u32x4*)(XB + off) = w;
;                     const f32x4 sq = x0 * x0 + x1 * x1;
;                     ss += (sq[0] + sq[1]) + (sq[2] + sq[3]);
.LBB0_462:
	s_waitcnt vmcnt(15)
	v_lshlrev_b32_e32 v238, 16, v130
	v_and_b32_e32 v239, 0xffff0000, v130
	v_lshlrev_b32_e32 v240, 16, v131
	v_and_b32_e32 v241, 0xffff0000, v131
	v_lshlrev_b32_e32 v242, 16, v132
	v_and_b32_e32 v243, 0xffff0000, v132
	v_lshlrev_b32_e32 v244, 16, v133
	v_and_b32_e32 v245, 0xffff0000, v133
	v_pk_fma_f32 v[126:127], v[126:127], 0.5, v[238:239] op_sel_hi:[1,0,1]
	v_pk_fma_f32 v[128:129], v[128:129], 0.5, v[240:241] op_sel_hi:[1,0,1]
	v_pk_fma_f32 v[122:123], v[122:123], 0.5, v[242:243] op_sel_hi:[1,0,1]
	v_pk_fma_f32 v[124:125], v[124:125], 0.5, v[244:245] op_sel_hi:[1,0,1]
	v_cvt_pk_bf16_f32 v130, v126, v127
	v_cvt_pk_bf16_f32 v131, v128, v129
	v_cvt_pk_bf16_f32 v132, v122, v123
	v_cvt_pk_bf16_f32 v133, v124, v125
	global_store_dwordx4 v[198:199], v[130:133], off
	v_pk_mul_f32 v[238:239], v[122:123], v[122:123]
	v_pk_mul_f32 v[240:241], v[124:125], v[124:125]
	v_pk_fma_f32 v[238:239], v[126:127], v[126:127], v[238:239]
	v_pk_fma_f32 v[240:241], v[128:129], v[128:129], v[240:241]
	s_nop 0
	v_add_f32_e32 v238, v238, v239
	v_add_f32_e32 v239, v240, v241
	v_add_f32_e32 v126, v238, v239
	s_waitcnt vmcnt(15)
	v_lshlrev_b32_e32 v238, 16, v134
	v_and_b32_e32 v239, 0xffff0000, v134
	v_lshlrev_b32_e32 v240, 16, v135
	v_and_b32_e32 v241, 0xffff0000, v135
	v_lshlrev_b32_e32 v242, 16, v136
	v_and_b32_e32 v243, 0xffff0000, v136
	v_lshlrev_b32_e32 v244, 16, v137
	v_and_b32_e32 v245, 0xffff0000, v137
	v_pk_fma_f32 v[118:119], v[118:119], 0.5, v[238:239] op_sel_hi:[1,0,1]
	v_pk_fma_f32 v[120:121], v[120:121], 0.5, v[240:241] op_sel_hi:[1,0,1]
	v_pk_fma_f32 v[114:115], v[114:115], 0.5, v[242:243] op_sel_hi:[1,0,1]
	v_pk_fma_f32 v[116:117], v[116:117], 0.5, v[244:245] op_sel_hi:[1,0,1]
	v_cvt_pk_bf16_f32 v134, v118, v119
	v_cvt_pk_bf16_f32 v135, v120, v121
	v_cvt_pk_bf16_f32 v136, v114, v115
	v_cvt_pk_bf16_f32 v137, v116, v117
	global_store_dwordx4 v[198:199], v[134:137], off offset:256
	v_pk_mul_f32 v[238:239], v[114:115], v[114:115]
	v_pk_mul_f32 v[240:241], v[116:117], v[116:117]
	v_pk_fma_f32 v[238:239], v[118:119], v[118:119], v[238:239]
	v_pk_fma_f32 v[240:241], v[120:121], v[120:121], v[240:241]
	s_nop 0
	v_add_f32_e32 v238, v238, v239
	v_add_f32_e32 v239, v240, v241
	v_add_f32_e32 v238, v238, v239
	v_add_f32_e32 v126, v126, v238
	v_lshl_add_u64 v[198:199], v[198:199], 0, s[18:19]
	s_waitcnt vmcnt(15)
	v_lshlrev_b32_e32 v238, 16, v138
	v_and_b32_e32 v239, 0xffff0000, v138
	v_lshlrev_b32_e32 v240, 16, v139
	v_and_b32_e32 v241, 0xffff0000, v139
	v_lshlrev_b32_e32 v242, 16, v140
	v_and_b32_e32 v243, 0xffff0000, v140
	v_lshlrev_b32_e32 v244, 16, v141
	v_and_b32_e32 v245, 0xffff0000, v141
	v_pk_fma_f32 v[110:111], v[110:111], 0.5, v[238:239] op_sel_hi:[1,0,1]
	v_pk_fma_f32 v[112:113], v[112:113], 0.5, v[240:241] op_sel_hi:[1,0,1]
	v_pk_fma_f32 v[106:107], v[106:107], 0.5, v[242:243] op_sel_hi:[1,0,1]
	v_pk_fma_f32 v[108:109], v[108:109], 0.5, v[244:245] op_sel_hi:[1,0,1]
	v_cvt_pk_bf16_f32 v138, v110, v111
	v_cvt_pk_bf16_f32 v139, v112, v113
	v_cvt_pk_bf16_f32 v140, v106, v107
	v_cvt_pk_bf16_f32 v141, v108, v109
	global_store_dwordx4 v[198:199], v[138:141], off
	v_pk_mul_f32 v[238:239], v[106:107], v[106:107]
	v_pk_mul_f32 v[240:241], v[108:109], v[108:109]
	v_pk_fma_f32 v[238:239], v[110:111], v[110:111], v[238:239]
	v_pk_fma_f32 v[240:241], v[112:113], v[112:113], v[240:241]
	s_nop 0
	v_add_f32_e32 v238, v238, v239
	v_add_f32_e32 v239, v240, v241
	v_add_f32_e32 v110, v238, v239
	s_waitcnt vmcnt(15)
	v_lshlrev_b32_e32 v238, 16, v142
	v_and_b32_e32 v239, 0xffff0000, v142
	v_lshlrev_b32_e32 v240, 16, v143
	v_and_b32_e32 v241, 0xffff0000, v143
	v_lshlrev_b32_e32 v242, 16, v144
	v_and_b32_e32 v243, 0xffff0000, v144
	v_lshlrev_b32_e32 v244, 16, v145
	v_and_b32_e32 v245, 0xffff0000, v145
	v_pk_fma_f32 v[102:103], v[102:103], 0.5, v[238:239] op_sel_hi:[1,0,1]
	v_pk_fma_f32 v[104:105], v[104:105], 0.5, v[240:241] op_sel_hi:[1,0,1]
	v_pk_fma_f32 v[98:99], v[98:99], 0.5, v[242:243] op_sel_hi:[1,0,1]
	v_pk_fma_f32 v[100:101], v[100:101], 0.5, v[244:245] op_sel_hi:[1,0,1]
	v_cvt_pk_bf16_f32 v142, v102, v103
	v_cvt_pk_bf16_f32 v143, v104, v105
	v_cvt_pk_bf16_f32 v144, v98, v99
	v_cvt_pk_bf16_f32 v145, v100, v101
	global_store_dwordx4 v[198:199], v[142:145], off offset:256
	v_pk_mul_f32 v[238:239], v[98:99], v[98:99]
	v_pk_mul_f32 v[240:241], v[100:101], v[100:101]
	v_pk_fma_f32 v[238:239], v[102:103], v[102:103], v[238:239]
	v_pk_fma_f32 v[240:241], v[104:105], v[104:105], v[240:241]
	s_nop 0
	v_add_f32_e32 v238, v238, v239
	v_add_f32_e32 v239, v240, v241
	v_add_f32_e32 v238, v238, v239
	v_add_f32_e32 v110, v110, v238
	v_lshl_add_u64 v[198:199], v[198:199], 0, s[18:19]
	s_waitcnt vmcnt(15)
	v_lshlrev_b32_e32 v238, 16, v146
	v_and_b32_e32 v239, 0xffff0000, v146
	v_lshlrev_b32_e32 v240, 16, v147
	v_and_b32_e32 v241, 0xffff0000, v147
	v_lshlrev_b32_e32 v242, 16, v148
	v_and_b32_e32 v243, 0xffff0000, v148
	v_lshlrev_b32_e32 v244, 16, v149
	v_and_b32_e32 v245, 0xffff0000, v149
	v_pk_fma_f32 v[94:95], v[94:95], 0.5, v[238:239] op_sel_hi:[1,0,1]
	v_pk_fma_f32 v[96:97], v[96:97], 0.5, v[240:241] op_sel_hi:[1,0,1]
	v_pk_fma_f32 v[90:91], v[90:91], 0.5, v[242:243] op_sel_hi:[1,0,1]
	v_pk_fma_f32 v[92:93], v[92:93], 0.5, v[244:245] op_sel_hi:[1,0,1]
	v_cvt_pk_bf16_f32 v146, v94, v95
	v_cvt_pk_bf16_f32 v147, v96, v97
	v_cvt_pk_bf16_f32 v148, v90, v91
	v_cvt_pk_bf16_f32 v149, v92, v93
	global_store_dwordx4 v[198:199], v[146:149], off
	v_pk_mul_f32 v[238:239], v[90:91], v[90:91]
	v_pk_mul_f32 v[240:241], v[92:93], v[92:93]
	v_pk_fma_f32 v[238:239], v[94:95], v[94:95], v[238:239]
	v_pk_fma_f32 v[240:241], v[96:97], v[96:97], v[240:241]
	s_nop 0
	v_add_f32_e32 v238, v238, v239
	v_add_f32_e32 v239, v240, v241
	v_add_f32_e32 v94, v238, v239
	s_waitcnt vmcnt(15)
; __device__ __forceinline__ unsigned cvt_pk_bf16(float lo, float hi) { f32x2_cv v = {lo, hi}; bf16x2_cv b = __builtin_convertvector(v, bf16x2_cv); return __builtin_bit_cast(unsigned, b); }
;     __device__ __forceinline__ void operator()(const f32x4 (&acc)[2][2][4][2], const Unit& u, int wr, int wc, int fr, int fq) const {
;     ...
;             for (int m = 0; m < 4; ++m) {
;                 const int row = row0 + ai * HALF + m * 16; float ss = 0.f;
; #pragma unroll
;                 for (int bj = 0; bj < 2; ++bj) {
;                     const size_t off = (size_t)row * 1024 + col0 + bj * HALF;
;                     const u32x4 v = xv[m][bj];
;                     f32x4 x0 = {__uint_as_float(v.x << 16), __uint_as_float(v.x & 0xffff0000u), __uint_as_float(v.y << 16), __uint_as_float(v.y & 0xffff0000u)};
;                     f32x4 x1 = {__uint_as_float(v.z << 16), __uint_as_float(v.z & 0xffff0000u), __uint_as_float(v.w << 16), __uint_as_float(v.w & 0xffff0000u)};
;                     x0 = x0 + acc[ai][bj][m][0] * alpha; x1 = x1 + acc[ai][bj][m][1] * alpha;
;                     u32x4 w; w.x = cvt_pk_bf16(x0[0], x0[1]); w.y = cvt_pk_bf16(x0[2], x0[3]); w.z = cvt_pk_bf16(x1[0], x1[1]); w.w = cvt_pk_bf16(x1[2], x1[3]);
;                     *(u32x4*)(XB + off) = w;
;                     const f32x4 sq = x0 * x0 + x1 * x1;
;                     ss += (sq[0] + sq[1]) + (sq[2] + sq[3]);
;                 }
	v_lshlrev_b32_e32 v238, 16, v150
	v_and_b32_e32 v239, 0xffff0000, v150
	v_lshlrev_b32_e32 v240, 16, v151
	v_and_b32_e32 v241, 0xffff0000, v151
	v_lshlrev_b32_e32 v242, 16, v152
	v_and_b32_e32 v243, 0xffff0000, v152
	v_lshlrev_b32_e32 v244, 16, v153
	v_and_b32_e32 v245, 0xffff0000, v153
	v_pk_fma_f32 v[86:87], v[86:87], 0.5, v[238:239] op_sel_hi:[1,0,1]
	v_pk_fma_f32 v[88:89], v[88:89], 0.5, v[240:241] op_sel_hi:[1,0,1]
	v_pk_fma_f32 v[82:83], v[82:83], 0.5, v[242:243] op_sel_hi:[1,0,1]
	v_pk_fma_f32 v[84:85], v[84:85], 0.5, v[244:245] op_sel_hi:[1,0,1]
	v_cvt_pk_bf16_f32 v150, v86, v87
	v_cvt_pk_bf16_f32 v151, v88, v89
	v_cvt_pk_bf16_f32 v152, v82, v83
	v_cvt_pk_bf16_f32 v153, v84, v85
	global_store_dwordx4 v[198:199], v[150:153], off offset:256
	v_pk_mul_f32 v[238:239], v[82:83], v[82:83]
	v_pk_mul_f32 v[240:241], v[84:85], v[84:85]
	v_pk_fma_f32 v[238:239], v[86:87], v[86:87], v[238:239]
	v_pk_fma_f32 v[240:241], v[88:89], v[88:89], v[240:241]
	s_nop 0
	v_add_f32_e32 v238, v238, v239
	v_add_f32_e32 v239, v240, v241
	v_add_f32_e32 v238, v238, v239
	v_add_f32_e32 v94, v94, v238
	v_lshl_add_u64 v[198:199], v[198:199], 0, s[18:19]
	s_waitcnt vmcnt(15)
	v_lshlrev_b32_e32 v238, 16, v154
	v_and_b32_e32 v239, 0xffff0000, v154
	v_lshlrev_b32_e32 v240, 16, v155
	v_and_b32_e32 v241, 0xffff0000, v155
	v_lshlrev_b32_e32 v242, 16, v156
	v_and_b32_e32 v243, 0xffff0000, v156
	v_lshlrev_b32_e32 v244, 16, v157
	v_and_b32_e32 v245, 0xffff0000, v157
	v_pk_fma_f32 v[78:79], v[78:79], 0.5, v[238:239] op_sel_hi:[1,0,1]
	v_pk_fma_f32 v[80:81], v[80:81], 0.5, v[240:241] op_sel_hi:[1,0,1]
	v_pk_fma_f32 v[74:75], v[74:75], 0.5, v[242:243] op_sel_hi:[1,0,1]
	v_pk_fma_f32 v[76:77], v[76:77], 0.5, v[244:245] op_sel_hi:[1,0,1]
	v_cvt_pk_bf16_f32 v154, v78, v79
	v_cvt_pk_bf16_f32 v155, v80, v81
	v_cvt_pk_bf16_f32 v156, v74, v75
	v_cvt_pk_bf16_f32 v157, v76, v77
	global_store_dwordx4 v[198:199], v[154:157], off
	v_pk_mul_f32 v[238:239], v[74:75], v[74:75]
	v_pk_mul_f32 v[240:241], v[76:77], v[76:77]
	v_pk_fma_f32 v[238:239], v[78:79], v[78:79], v[238:239]
	v_pk_fma_f32 v[240:241], v[80:81], v[80:81], v[240:241]
	s_nop 0
	v_add_f32_e32 v238, v238, v239
	v_add_f32_e32 v239, v240, v241
	v_add_f32_e32 v78, v238, v239
	s_waitcnt vmcnt(15)
	v_lshlrev_b32_e32 v238, 16, v218
	v_and_b32_e32 v239, 0xffff0000, v218
	v_lshlrev_b32_e32 v240, 16, v219
	v_and_b32_e32 v241, 0xffff0000, v219
	v_lshlrev_b32_e32 v242, 16, v220
	v_and_b32_e32 v243, 0xffff0000, v220
	v_lshlrev_b32_e32 v244, 16, v221
	v_and_b32_e32 v245, 0xffff0000, v221
	v_pk_fma_f32 v[70:71], v[70:71], 0.5, v[238:239] op_sel_hi:[1,0,1]
	v_pk_fma_f32 v[72:73], v[72:73], 0.5, v[240:241] op_sel_hi:[1,0,1]
	v_pk_fma_f32 v[66:67], v[66:67], 0.5, v[242:243] op_sel_hi:[1,0,1]
	v_pk_fma_f32 v[68:69], v[68:69], 0.5, v[244:245] op_sel_hi:[1,0,1]
	v_cvt_pk_bf16_f32 v218, v70, v71
	v_cvt_pk_bf16_f32 v219, v72, v73
	v_cvt_pk_bf16_f32 v220, v66, v67
	v_cvt_pk_bf16_f32 v221, v68, v69
	global_store_dwordx4 v[198:199], v[218:221], off offset:256
	v_pk_mul_f32 v[238:239], v[66:67], v[66:67]
	v_pk_mul_f32 v[240:241], v[68:69], v[68:69]
	v_pk_fma_f32 v[238:239], v[70:71], v[70:71], v[238:239]
	v_pk_fma_f32 v[240:241], v[72:73], v[72:73], v[240:241]
	s_nop 0
	v_add_f32_e32 v238, v238, v239
	v_add_f32_e32 v239, v240, v241
	v_add_f32_e32 v238, v238, v239
	v_add_f32_e32 v78, v78, v238
	v_lshl_add_u64 v[198:199], v[198:199], 0, s[88:89]
	s_waitcnt vmcnt(15)
	v_lshlrev_b32_e32 v238, 16, v182
	v_and_b32_e32 v239, 0xffff0000, v182
	v_lshlrev_b32_e32 v240, 16, v183
	v_and_b32_e32 v241, 0xffff0000, v183
	v_lshlrev_b32_e32 v242, 16, v184
	v_and_b32_e32 v243, 0xffff0000, v184
	v_lshlrev_b32_e32 v244, 16, v185
	v_and_b32_e32 v245, 0xffff0000, v185
	v_pk_fma_f32 v[62:63], v[62:63], 0.5, v[238:239] op_sel_hi:[1,0,1]
	v_pk_fma_f32 v[64:65], v[64:65], 0.5, v[240:241] op_sel_hi:[1,0,1]
	v_pk_fma_f32 v[58:59], v[58:59], 0.5, v[242:243] op_sel_hi:[1,0,1]
	v_pk_fma_f32 v[60:61], v[60:61], 0.5, v[244:245] op_sel_hi:[1,0,1]
	v_cvt_pk_bf16_f32 v182, v62, v63
	v_cvt_pk_bf16_f32 v183, v64, v65
	v_cvt_pk_bf16_f32 v184, v58, v59
	v_cvt_pk_bf16_f32 v185, v60, v61
	global_store_dwordx4 v[198:199], v[182:185], off
	v_pk_mul_f32 v[238:239], v[58:59], v[58:59]
	v_pk_mul_f32 v[240:241], v[60:61], v[60:61]
	v_pk_fma_f32 v[238:239], v[62:63], v[62:63], v[238:239]
	v_pk_fma_f32 v[240:241], v[64:65], v[64:65], v[240:241]
	s_nop 0
	v_add_f32_e32 v238, v238, v239
	v_add_f32_e32 v239, v240, v241
	v_add_f32_e32 v62, v238, v239
	s_waitcnt vmcnt(15)
	v_lshlrev_b32_e32 v238, 16, v186
	v_and_b32_e32 v239, 0xffff0000, v186
	v_lshlrev_b32_e32 v240, 16, v187
	v_and_b32_e32 v241, 0xffff0000, v187
	v_lshlrev_b32_e32 v242, 16, v188
	v_and_b32_e32 v243, 0xffff0000, v188
	v_lshlrev_b32_e32 v244, 16, v189
	v_and_b32_e32 v245, 0xffff0000, v189
	v_pk_fma_f32 v[54:55], v[54:55], 0.5, v[238:239] op_sel_hi:[1,0,1]
	v_pk_fma_f32 v[56:57], v[56:57], 0.5, v[240:241] op_sel_hi:[1,0,1]
	v_pk_fma_f32 v[50:51], v[50:51], 0.5, v[242:243] op_sel_hi:[1,0,1]
	v_pk_fma_f32 v[52:53], v[52:53], 0.5, v[244:245] op_sel_hi:[1,0,1]
	v_cvt_pk_bf16_f32 v186, v54, v55
	v_cvt_pk_bf16_f32 v187, v56, v57
	v_cvt_pk_bf16_f32 v188, v50, v51
	v_cvt_pk_bf16_f32 v189, v52, v53
	global_store_dwordx4 v[198:199], v[186:189], off offset:256
	v_pk_mul_f32 v[238:239], v[50:51], v[50:51]
	v_pk_mul_f32 v[240:241], v[52:53], v[52:53]
	v_pk_fma_f32 v[238:239], v[54:55], v[54:55], v[238:239]
	v_pk_fma_f32 v[240:241], v[56:57], v[56:57], v[240:241]
	s_nop 0
	v_add_f32_e32 v238, v238, v239
	v_add_f32_e32 v239, v240, v241
	v_add_f32_e32 v238, v238, v239
	v_add_f32_e32 v62, v62, v238
	v_lshl_add_u64 v[198:199], v[198:199], 0, s[18:19]
	s_waitcnt vmcnt(15)
; __device__ __forceinline__ unsigned cvt_pk_bf16(float lo, float hi) { f32x2_cv v = {lo, hi}; bf16x2_cv b = __builtin_convertvector(v, bf16x2_cv); return __builtin_bit_cast(unsigned, b); }
;     __device__ __forceinline__ void operator()(const f32x4 (&acc)[2][2][4][2], const Unit& u, int wr, int wc, int fr, int fq) const {
;     ...
;             for (int m = 0; m < 4; ++m) {
;                 const int row = row0 + ai * HALF + m * 16; float ss = 0.f;
; #pragma unroll
;                 for (int bj = 0; bj < 2; ++bj) {
;                     const size_t off = (size_t)row * 1024 + col0 + bj * HALF;
;                     const u32x4 v = xv[m][bj];
;                     f32x4 x0 = {__uint_as_float(v.x << 16), __uint_as_float(v.x & 0xffff0000u), __uint_as_float(v.y << 16), __uint_as_float(v.y & 0xffff0000u)};
;                     f32x4 x1 = {__uint_as_float(v.z << 16), __uint_as_float(v.z & 0xffff0000u), __uint_as_float(v.w << 16), __uint_as_float(v.w & 0xffff0000u)};
;                     x0 = x0 + acc[ai][bj][m][0] * alpha; x1 = x1 + acc[ai][bj][m][1] * alpha;
;                     u32x4 w; w.x = cvt_pk_bf16(x0[0], x0[1]); w.y = cvt_pk_bf16(x0[2], x0[3]); w.z = cvt_pk_bf16(x1[0], x1[1]); w.w = cvt_pk_bf16(x1[2], x1[3]);
;                     *(u32x4*)(XB + off) = w;
;                     const f32x4 sq = x0 * x0 + x1 * x1;
;                     ss += (sq[0] + sq[1]) + (sq[2] + sq[3]);
;                 }
	v_lshlrev_b32_e32 v238, 16, v190
	v_and_b32_e32 v239, 0xffff0000, v190
	v_lshlrev_b32_e32 v240, 16, v191
	v_and_b32_e32 v241, 0xffff0000, v191
	v_lshlrev_b32_e32 v242, 16, v192
	v_and_b32_e32 v243, 0xffff0000, v192
	v_lshlrev_b32_e32 v244, 16, v193
	v_and_b32_e32 v245, 0xffff0000, v193
	v_pk_fma_f32 v[46:47], v[46:47], 0.5, v[238:239] op_sel_hi:[1,0,1]
	v_pk_fma_f32 v[48:49], v[48:49], 0.5, v[240:241] op_sel_hi:[1,0,1]
	v_pk_fma_f32 v[42:43], v[42:43], 0.5, v[242:243] op_sel_hi:[1,0,1]
	v_pk_fma_f32 v[44:45], v[44:45], 0.5, v[244:245] op_sel_hi:[1,0,1]
	v_cvt_pk_bf16_f32 v190, v46, v47
	v_cvt_pk_bf16_f32 v191, v48, v49
	v_cvt_pk_bf16_f32 v192, v42, v43
	v_cvt_pk_bf16_f32 v193, v44, v45
	global_store_dwordx4 v[198:199], v[190:193], off
	v_pk_mul_f32 v[238:239], v[42:43], v[42:43]
	v_pk_mul_f32 v[240:241], v[44:45], v[44:45]
	v_pk_fma_f32 v[238:239], v[46:47], v[46:47], v[238:239]
	v_pk_fma_f32 v[240:241], v[48:49], v[48:49], v[240:241]
	s_nop 0
	v_add_f32_e32 v238, v238, v239
	v_add_f32_e32 v239, v240, v241
	v_add_f32_e32 v46, v238, v239
	s_waitcnt vmcnt(15)
	v_lshlrev_b32_e32 v238, 16, v194
	v_and_b32_e32 v239, 0xffff0000, v194
	v_lshlrev_b32_e32 v240, 16, v195
	v_and_b32_e32 v241, 0xffff0000, v195
	v_lshlrev_b32_e32 v242, 16, v196
	v_and_b32_e32 v243, 0xffff0000, v196
	v_lshlrev_b32_e32 v244, 16, v197
	v_and_b32_e32 v245, 0xffff0000, v197
	v_pk_fma_f32 v[38:39], v[38:39], 0.5, v[238:239] op_sel_hi:[1,0,1]
	v_pk_fma_f32 v[40:41], v[40:41], 0.5, v[240:241] op_sel_hi:[1,0,1]
	v_pk_fma_f32 v[34:35], v[34:35], 0.5, v[242:243] op_sel_hi:[1,0,1]
	v_pk_fma_f32 v[36:37], v[36:37], 0.5, v[244:245] op_sel_hi:[1,0,1]
	v_cvt_pk_bf16_f32 v194, v38, v39
	v_cvt_pk_bf16_f32 v195, v40, v41
	v_cvt_pk_bf16_f32 v196, v34, v35
	v_cvt_pk_bf16_f32 v197, v36, v37
	global_store_dwordx4 v[198:199], v[194:197], off offset:256
	v_pk_mul_f32 v[238:239], v[34:35], v[34:35]
	v_pk_mul_f32 v[240:241], v[36:37], v[36:37]
	v_pk_fma_f32 v[238:239], v[38:39], v[38:39], v[238:239]
	v_pk_fma_f32 v[240:241], v[40:41], v[40:41], v[240:241]
	s_nop 0
	v_add_f32_e32 v238, v238, v239
	v_add_f32_e32 v239, v240, v241
	v_add_f32_e32 v238, v238, v239
	v_add_f32_e32 v46, v46, v238
	v_lshl_add_u64 v[198:199], v[198:199], 0, s[18:19]
	s_waitcnt vmcnt(15)
	v_lshlrev_b32_e32 v238, 16, v222
	v_and_b32_e32 v239, 0xffff0000, v222
	v_lshlrev_b32_e32 v240, 16, v223
	v_and_b32_e32 v241, 0xffff0000, v223
	v_lshlrev_b32_e32 v242, 16, v224
	v_and_b32_e32 v243, 0xffff0000, v224
	v_lshlrev_b32_e32 v244, 16, v225
	v_and_b32_e32 v245, 0xffff0000, v225
	v_pk_fma_f32 v[30:31], v[30:31], 0.5, v[238:239] op_sel_hi:[1,0,1]
	v_pk_fma_f32 v[32:33], v[32:33], 0.5, v[240:241] op_sel_hi:[1,0,1]
	v_pk_fma_f32 v[26:27], v[26:27], 0.5, v[242:243] op_sel_hi:[1,0,1]
	v_pk_fma_f32 v[28:29], v[28:29], 0.5, v[244:245] op_sel_hi:[1,0,1]
	v_cvt_pk_bf16_f32 v222, v30, v31
	v_cvt_pk_bf16_f32 v223, v32, v33
	v_cvt_pk_bf16_f32 v224, v26, v27
	v_cvt_pk_bf16_f32 v225, v28, v29
	global_store_dwordx4 v[198:199], v[222:225], off
	v_pk_mul_f32 v[238:239], v[26:27], v[26:27]
	v_pk_mul_f32 v[240:241], v[28:29], v[28:29]
	v_pk_fma_f32 v[238:239], v[30:31], v[30:31], v[238:239]
	v_pk_fma_f32 v[240:241], v[32:33], v[32:33], v[240:241]
	s_nop 0
	v_add_f32_e32 v238, v238, v239
	v_add_f32_e32 v239, v240, v241
	v_add_f32_e32 v30, v238, v239
	s_waitcnt vmcnt(15)
	v_lshlrev_b32_e32 v238, 16, v226
	v_and_b32_e32 v239, 0xffff0000, v226
	v_lshlrev_b32_e32 v240, 16, v227
	v_and_b32_e32 v241, 0xffff0000, v227
	v_lshlrev_b32_e32 v242, 16, v228
	v_and_b32_e32 v243, 0xffff0000, v228
	v_lshlrev_b32_e32 v244, 16, v229
	v_and_b32_e32 v245, 0xffff0000, v229
	v_pk_fma_f32 v[22:23], v[22:23], 0.5, v[238:239] op_sel_hi:[1,0,1]
	v_pk_fma_f32 v[24:25], v[24:25], 0.5, v[240:241] op_sel_hi:[1,0,1]
	v_pk_fma_f32 v[18:19], v[18:19], 0.5, v[242:243] op_sel_hi:[1,0,1]
	v_pk_fma_f32 v[20:21], v[20:21], 0.5, v[244:245] op_sel_hi:[1,0,1]
	v_cvt_pk_bf16_f32 v226, v22, v23
	v_cvt_pk_bf16_f32 v227, v24, v25
	v_cvt_pk_bf16_f32 v228, v18, v19
	v_cvt_pk_bf16_f32 v229, v20, v21
	global_store_dwordx4 v[198:199], v[226:229], off offset:256
	v_pk_mul_f32 v[238:239], v[18:19], v[18:19]
	v_pk_mul_f32 v[240:241], v[20:21], v[20:21]
	v_pk_fma_f32 v[238:239], v[22:23], v[22:23], v[238:239]
	v_pk_fma_f32 v[240:241], v[24:25], v[24:25], v[240:241]
	s_nop 0
	v_add_f32_e32 v238, v238, v239
	v_add_f32_e32 v239, v240, v241
	v_add_f32_e32 v238, v238, v239
	v_add_f32_e32 v30, v30, v238
	v_lshl_add_u64 v[198:199], v[198:199], 0, s[18:19]
	s_waitcnt vmcnt(15)
;     __device__ __forceinline__ void operator()(const f32x4 (&acc)[2][2][4][2], const Unit& u, int wr, int wc, int fr, int fq) const {
;     ...
;                     const f32x4 sq = x0 * x0 + x1 * x1;
;                     ss += (sq[0] + sq[1]) + (sq[2] + sq[3]);
;                 }
;                 ss += __shfl_xor(ss, 16); ss += __shfl_xor(ss, 32);
;                 if (fq == 0) rsp_out[(size_t)row * 16 + u.pn * 4 + wc] = ss;
;             }
	v_lshlrev_b32_e32 v238, 16, v230
	v_and_b32_e32 v239, 0xffff0000, v230
	v_lshlrev_b32_e32 v240, 16, v231
	v_and_b32_e32 v241, 0xffff0000, v231
	v_lshlrev_b32_e32 v242, 16, v232
	v_and_b32_e32 v243, 0xffff0000, v232
	v_lshlrev_b32_e32 v244, 16, v233
	v_and_b32_e32 v245, 0xffff0000, v233
	v_pk_fma_f32 v[14:15], v[14:15], 0.5, v[238:239] op_sel_hi:[1,0,1]
	v_pk_fma_f32 v[16:17], v[16:17], 0.5, v[240:241] op_sel_hi:[1,0,1]
	v_pk_fma_f32 v[10:11], v[10:11], 0.5, v[242:243] op_sel_hi:[1,0,1]
	v_pk_fma_f32 v[12:13], v[12:13], 0.5, v[244:245] op_sel_hi:[1,0,1]
	v_cvt_pk_bf16_f32 v230, v14, v15
	v_cvt_pk_bf16_f32 v231, v16, v17
	v_cvt_pk_bf16_f32 v232, v10, v11
	v_cvt_pk_bf16_f32 v233, v12, v13
	global_store_dwordx4 v[198:199], v[230:233], off
	v_pk_mul_f32 v[238:239], v[10:11], v[10:11]
	v_pk_mul_f32 v[240:241], v[12:13], v[12:13]
	v_pk_fma_f32 v[238:239], v[14:15], v[14:15], v[238:239]
	v_pk_fma_f32 v[240:241], v[16:17], v[16:17], v[240:241]
	s_nop 0
	v_add_f32_e32 v238, v238, v239
	v_add_f32_e32 v239, v240, v241
	v_add_f32_e32 v14, v238, v239
	s_waitcnt vmcnt(15)
	v_lshlrev_b32_e32 v238, 16, v234
	v_and_b32_e32 v239, 0xffff0000, v234
	v_lshlrev_b32_e32 v240, 16, v235
	v_and_b32_e32 v241, 0xffff0000, v235
	v_lshlrev_b32_e32 v242, 16, v236
	v_and_b32_e32 v243, 0xffff0000, v236
	v_lshlrev_b32_e32 v244, 16, v237
	v_and_b32_e32 v245, 0xffff0000, v237
	v_pk_fma_f32 v[6:7], v[6:7], 0.5, v[238:239] op_sel_hi:[1,0,1]
	v_pk_fma_f32 v[8:9], v[8:9], 0.5, v[240:241] op_sel_hi:[1,0,1]
	v_pk_fma_f32 v[2:3], v[2:3], 0.5, v[242:243] op_sel_hi:[1,0,1]
	v_pk_fma_f32 v[4:5], v[4:5], 0.5, v[244:245] op_sel_hi:[1,0,1]
	v_cvt_pk_bf16_f32 v234, v6, v7
	v_cvt_pk_bf16_f32 v235, v8, v9
	v_cvt_pk_bf16_f32 v236, v2, v3
	v_cvt_pk_bf16_f32 v237, v4, v5
	global_store_dwordx4 v[198:199], v[234:237], off offset:256
	v_pk_mul_f32 v[238:239], v[2:3], v[2:3]
	v_pk_mul_f32 v[240:241], v[4:5], v[4:5]
	v_pk_fma_f32 v[238:239], v[6:7], v[6:7], v[238:239]
	v_pk_fma_f32 v[240:241], v[8:9], v[8:9], v[240:241]
	s_nop 0
	v_add_f32_e32 v238, v238, v239
	v_add_f32_e32 v239, v240, v241
	v_add_f32_e32 v238, v238, v239
	v_add_f32_e32 v14, v14, v238
	ds_bpermute_b32 v127, v215, v126
	ds_bpermute_b32 v111, v215, v110
	ds_bpermute_b32 v95, v215, v94
	ds_bpermute_b32 v79, v215, v78
	ds_bpermute_b32 v63, v215, v62
	ds_bpermute_b32 v47, v215, v46
	ds_bpermute_b32 v31, v215, v30
	ds_bpermute_b32 v15, v215, v14
	s_waitcnt lgkmcnt(0)
	v_add_f32_e32 v126, v126, v127
	v_add_f32_e32 v110, v110, v111
	v_add_f32_e32 v94, v94, v95
	v_add_f32_e32 v78, v78, v79
	v_add_f32_e32 v62, v62, v63
	v_add_f32_e32 v46, v46, v47
	v_add_f32_e32 v30, v30, v31
	v_add_f32_e32 v14, v14, v15
	ds_bpermute_b32 v127, v216, v126
	ds_bpermute_b32 v111, v216, v110
	ds_bpermute_b32 v95, v216, v94
	ds_bpermute_b32 v79, v216, v78
	ds_bpermute_b32 v63, v216, v62
	ds_bpermute_b32 v47, v216, v46
	ds_bpermute_b32 v31, v216, v30
	ds_bpermute_b32 v15, v216, v14
	s_waitcnt lgkmcnt(0)
	v_add_f32_e32 v126, v126, v127
	v_add_f32_e32 v110, v110, v111
	v_add_f32_e32 v94, v94, v95
	v_add_f32_e32 v78, v78, v79
	v_add_f32_e32 v62, v62, v63
	v_add_f32_e32 v46, v46, v47
	v_add_f32_e32 v30, v30, v31
	v_add_f32_e32 v14, v14, v15
	s_lshl_b32 s18, s45, 4
	s_lshl_b32 s88, s34, 2
	s_add_i32 s18, s18, s88
	v_lshlrev_b32_e32 v246, 6, v217
	v_mov_b32_e32 v247, 0
	v_lshl_add_u64 v[246:247], s[76:77], 0, v[246:247]
	v_lshl_add_u64 v[246:247], v[246:247], 0, s[18:19]
	s_mov_b32 s18, 0x2000
	v_lshl_add_u64 v[198:199], v[246:247], 0, s[18:19]
	s_and_saveexec_b64 s[20:21], s[4:5]
	global_store_dword v[246:247], v126, off
	global_store_dword v[246:247], v110, off offset:1024
	global_store_dword v[246:247], v94, off offset:2048
	global_store_dword v[246:247], v78, off offset:3072
	global_store_dword v[198:199], v62, off
	global_store_dword v[198:199], v46, off offset:1024
	global_store_dword v[198:199], v30, off offset:2048
	global_store_dword v[198:199], v14, off offset:3072
	s_or_b64 exec, exec, s[20:21]
	s_and_b64 vcc, exec, s[6:7]
	s_mov_b64 s[6:7], -1
	s_cbranch_vccnz .LBB0_447
	s_andn2_b64 vcc, exec, s[12:13]
	s_cbranch_vccnz .LBB0_446
	s_barrier
	s_branch .LBB0_446
